# dilated attention: row-max reduction without the 66 self-max canonicalisations per item (consumers read the scores directly)
# baseline (speedup 1.0000x reference)
.LBB0_1293:
	v_lshl_or_b32 v82, s73, 4, v32
	v_readlane_b32 s8, v252, 57
	s_nop 0
	v_max_i32_e32 v16, 0x80, v82
	v_readlane_b32 s9, v252, 58
	v_lshrrev_b32_e32 v18, 2, v98
	v_add_u32_e32 v17, 0x80, v82
	v_cndmask_b32_e64 v16, v82, v16, s[8:9]
	v_and_b32_e32 v83, 12, v18
	v_cmp_lt_i32_e32 vcc, v83, v16
	v_cmp_gt_i32_e64 s[10:11], v83, v17
	s_or_b64 vcc, vcc, s[10:11]
	v_or_b32_e32 v19, 1, v83
	v_cndmask_b32_e32 v12, v12, v225, vcc
	v_cmp_lt_i32_e32 vcc, v19, v16
	v_cmp_ge_i32_e64 s[10:11], v83, v17
	s_or_b64 vcc, vcc, s[10:11]
	v_or_b32_e32 v19, 2, v83
	v_cndmask_b32_e32 v13, v13, v225, vcc
	v_cmp_lt_i32_e32 vcc, v19, v16
	v_cmp_gt_i32_e64 s[10:11], v19, v17
	s_or_b64 vcc, vcc, s[10:11]
	v_or_b32_e32 v19, 3, v18
	v_cndmask_b32_e32 v14, v14, v225, vcc
	v_cmp_lt_i32_e32 vcc, v19, v16
	v_cmp_gt_i32_e64 s[10:11], v19, v17
	s_or_b64 vcc, vcc, s[10:11]
	v_or_b32_e32 v19, 16, v83
	v_cndmask_b32_e32 v15, v15, v225, vcc
	v_cmp_lt_i32_e32 vcc, v19, v16
	v_cmp_gt_i32_e64 s[10:11], v19, v17
	s_or_b64 vcc, vcc, s[10:11]
	v_or_b32_e32 v19, 17, v83
	v_cndmask_b32_e32 v8, v8, v225, vcc
	v_cmp_lt_i32_e32 vcc, v19, v16
	v_cmp_gt_i32_e64 s[10:11], v19, v17
	s_or_b64 vcc, vcc, s[10:11]
	v_or_b32_e32 v19, 18, v83
	v_cndmask_b32_e32 v9, v9, v225, vcc
	v_cmp_lt_i32_e32 vcc, v19, v16
	v_cmp_gt_i32_e64 s[10:11], v19, v17
	s_or_b64 vcc, vcc, s[10:11]
	v_or_b32_e32 v19, 19, v18
	v_cndmask_b32_e32 v10, v10, v225, vcc
	v_cmp_lt_i32_e32 vcc, v19, v16
	v_cmp_gt_i32_e64 s[10:11], v19, v17
	s_or_b64 vcc, vcc, s[10:11]
	v_or_b32_e32 v19, 32, v83
	v_cndmask_b32_e32 v11, v11, v225, vcc
	v_cmp_lt_i32_e32 vcc, v19, v16
	v_cmp_gt_i32_e64 s[10:11], v19, v17
	s_or_b64 vcc, vcc, s[10:11]
	v_or_b32_e32 v20, 33, v83
	v_cndmask_b32_e32 v19, v42, v225, vcc
	v_cmp_lt_i32_e32 vcc, v20, v16
	v_cmp_gt_i32_e64 s[10:11], v20, v17
	s_or_b64 vcc, vcc, s[10:11]
	v_or_b32_e32 v21, 34, v83
	v_cndmask_b32_e32 v20, v43, v225, vcc
	v_cmp_lt_i32_e32 vcc, v21, v16
	v_cmp_gt_i32_e64 s[10:11], v21, v17
	s_or_b64 vcc, vcc, s[10:11]
	v_or_b32_e32 v22, 35, v18
	v_cndmask_b32_e32 v21, v44, v225, vcc
	v_cmp_lt_i32_e32 vcc, v22, v16
	v_cmp_gt_i32_e64 s[10:11], v22, v17
	s_or_b64 vcc, vcc, s[10:11]
	v_or_b32_e32 v23, 48, v83
	v_cndmask_b32_e32 v22, v45, v225, vcc
	v_cmp_lt_i32_e32 vcc, v23, v16
	v_cmp_gt_i32_e64 s[10:11], v23, v17
	s_or_b64 vcc, vcc, s[10:11]
	v_or_b32_e32 v23, 49, v83
	v_cndmask_b32_e32 v0, v0, v225, vcc
	v_cmp_lt_i32_e32 vcc, v23, v16
	v_cmp_gt_i32_e64 s[10:11], v23, v17
	s_or_b64 vcc, vcc, s[10:11]
	v_or_b32_e32 v23, 50, v83
	v_cndmask_b32_e32 v1, v1, v225, vcc
	v_cmp_lt_i32_e32 vcc, v23, v16
	v_cmp_gt_i32_e64 s[10:11], v23, v17
	s_or_b64 vcc, vcc, s[10:11]
	v_or_b32_e32 v23, 51, v18
	v_cndmask_b32_e32 v2, v2, v225, vcc
	v_cmp_lt_i32_e32 vcc, v23, v16
	v_cmp_gt_i32_e64 s[10:11], v23, v17
	s_or_b64 vcc, vcc, s[10:11]
	v_or_b32_e32 v23, 64, v83
	v_cndmask_b32_e32 v3, v3, v225, vcc
	v_cmp_lt_i32_e32 vcc, v23, v16
	v_cmp_gt_i32_e64 s[10:11], v23, v17
	s_or_b64 vcc, vcc, s[10:11]
	v_or_b32_e32 v24, 0x41, v83
	v_cndmask_b32_e32 v23, v46, v225, vcc
	v_cmp_lt_i32_e32 vcc, v24, v16
	v_cmp_gt_i32_e64 s[10:11], v24, v17
	s_or_b64 vcc, vcc, s[10:11]
	v_or_b32_e32 v25, 0x42, v83
	v_cndmask_b32_e32 v24, v47, v225, vcc
	v_cmp_lt_i32_e32 vcc, v25, v16
	v_cmp_gt_i32_e64 s[10:11], v25, v17
	s_or_b64 vcc, vcc, s[10:11]
	v_or_b32_e32 v26, 0x43, v18
	v_cndmask_b32_e32 v25, v48, v225, vcc
	v_cmp_lt_i32_e32 vcc, v26, v16
	v_cmp_gt_i32_e64 s[10:11], v26, v17
	s_or_b64 vcc, vcc, s[10:11]
	v_or_b32_e32 v27, 0x50, v83
	v_cndmask_b32_e32 v26, v49, v225, vcc
	v_cmp_lt_i32_e32 vcc, v27, v16
	v_cmp_gt_i32_e64 s[10:11], v27, v17
	s_or_b64 vcc, vcc, s[10:11]
	v_or_b32_e32 v28, 0x51, v83
	v_cndmask_b32_e32 v27, v38, v225, vcc
	v_cmp_lt_i32_e32 vcc, v28, v16
	v_cmp_gt_i32_e64 s[10:11], v28, v17
	s_or_b64 vcc, vcc, s[10:11]
	v_or_b32_e32 v29, 0x52, v83
	v_cndmask_b32_e32 v28, v39, v225, vcc
	v_cmp_lt_i32_e32 vcc, v29, v16
	v_cmp_gt_i32_e64 s[10:11], v29, v17
	s_or_b64 vcc, vcc, s[10:11]
	v_or_b32_e32 v30, 0x53, v18
	v_cndmask_b32_e32 v29, v40, v225, vcc
	v_cmp_lt_i32_e32 vcc, v30, v16
	v_cmp_gt_i32_e64 s[10:11], v30, v17
	s_or_b64 vcc, vcc, s[10:11]
	v_or_b32_e32 v31, 0x60, v83
	v_cndmask_b32_e32 v30, v41, v225, vcc
	v_cmp_lt_i32_e32 vcc, v31, v16
	v_cmp_gt_i32_e64 s[10:11], v31, v17
	s_or_b64 vcc, vcc, s[10:11]
	v_or_b32_e32 v38, 0x61, v83
	v_cndmask_b32_e32 v31, v58, v225, vcc
	v_cmp_lt_i32_e32 vcc, v38, v16
	v_cmp_gt_i32_e64 s[10:11], v38, v17
	s_or_b64 vcc, vcc, s[10:11]
	v_or_b32_e32 v38, 0x62, v83
	v_cndmask_b32_e32 v39, v59, v225, vcc
	v_cmp_lt_i32_e32 vcc, v38, v16
	v_cmp_gt_i32_e64 s[10:11], v38, v17
	s_or_b64 vcc, vcc, s[10:11]
	v_or_b32_e32 v38, 0x63, v18
	v_cndmask_b32_e32 v40, v60, v225, vcc
	v_cmp_lt_i32_e32 vcc, v38, v16
	v_cmp_gt_i32_e64 s[10:11], v38, v17
	s_or_b64 vcc, vcc, s[10:11]
	v_or_b32_e32 v38, 0x70, v83
	v_cndmask_b32_e32 v41, v61, v225, vcc
	v_cmp_lt_i32_e32 vcc, v38, v16
	v_cmp_gt_i32_e64 s[10:11], v38, v17
	s_or_b64 vcc, vcc, s[10:11]
	v_or_b32_e32 v38, 0x71, v83
	v_cndmask_b32_e32 v4, v4, v225, vcc
	v_cmp_lt_i32_e32 vcc, v38, v16
	v_cmp_gt_i32_e64 s[10:11], v38, v17
	s_or_b64 vcc, vcc, s[10:11]
	v_or_b32_e32 v38, 0x72, v83
	v_cndmask_b32_e32 v5, v5, v225, vcc
	v_cmp_lt_i32_e32 vcc, v38, v16
	v_cmp_gt_i32_e64 s[10:11], v38, v17
	s_or_b64 vcc, vcc, s[10:11]
	v_or_b32_e32 v38, 0x73, v18
	v_cndmask_b32_e32 v6, v6, v225, vcc
	v_cmp_lt_i32_e32 vcc, v38, v16
	v_cmp_gt_i32_e64 s[10:11], v38, v17
	s_or_b64 vcc, vcc, s[10:11]
	v_or_b32_e32 v38, 0x80, v83
	v_cndmask_b32_e32 v7, v7, v225, vcc
	v_cmp_lt_i32_e32 vcc, v38, v16
	v_cmp_gt_i32_e64 s[10:11], v83, v82
	s_or_b64 vcc, vcc, s[10:11]
	v_or_b32_e32 v38, 0x81, v83
	v_cndmask_b32_e32 v42, v62, v225, vcc
	v_cmp_lt_i32_e32 vcc, v38, v16
	v_cmp_gt_i32_e64 s[10:11], v38, v17
	s_or_b64 vcc, vcc, s[10:11]
	v_or_b32_e32 v38, 0x82, v83
	v_cndmask_b32_e32 v43, v63, v225, vcc
	v_cmp_lt_i32_e32 vcc, v38, v16
	v_cmp_gt_i32_e64 s[10:11], v38, v17
	s_or_b64 vcc, vcc, s[10:11]
	v_or_b32_e32 v38, 0x83, v18
	v_cndmask_b32_e32 v44, v64, v225, vcc
	v_cmp_lt_i32_e32 vcc, v38, v16
	v_cmp_gt_i32_e64 s[10:11], v38, v17
	s_or_b64 vcc, vcc, s[10:11]
	v_or_b32_e32 v38, 0x90, v83
	v_cndmask_b32_e32 v45, v65, v225, vcc
	v_cmp_lt_i32_e32 vcc, v38, v16
	v_cmp_gt_i32_e64 s[10:11], v38, v17
	s_or_b64 vcc, vcc, s[10:11]
	v_or_b32_e32 v38, 0x91, v83
	v_cndmask_b32_e32 v46, v54, v225, vcc
	v_cmp_lt_i32_e32 vcc, v38, v16
	v_cmp_gt_i32_e64 s[10:11], v38, v17
	s_or_b64 vcc, vcc, s[10:11]
	v_or_b32_e32 v38, 0x92, v83
	v_cndmask_b32_e32 v47, v55, v225, vcc
	v_cmp_lt_i32_e32 vcc, v38, v16
	v_cmp_gt_i32_e64 s[10:11], v38, v17
	s_or_b64 vcc, vcc, s[10:11]
	v_or_b32_e32 v38, 0x93, v18
	v_cndmask_b32_e32 v48, v56, v225, vcc
	v_cmp_lt_i32_e32 vcc, v38, v16
	v_cmp_gt_i32_e64 s[10:11], v38, v17
	s_or_b64 vcc, vcc, s[10:11]
	v_or_b32_e32 v38, 0xa0, v83
	v_cndmask_b32_e32 v49, v57, v225, vcc
	v_cmp_lt_i32_e32 vcc, v38, v16
	v_cmp_gt_i32_e64 s[10:11], v38, v17
	s_or_b64 vcc, vcc, s[10:11]
	v_or_b32_e32 v38, 0xa1, v83
	v_cndmask_b32_e32 v54, v70, v225, vcc
	v_cmp_lt_i32_e32 vcc, v38, v16
	v_cmp_gt_i32_e64 s[10:11], v38, v17
	s_or_b64 vcc, vcc, s[10:11]
	v_or_b32_e32 v38, 0xa2, v83
	v_cndmask_b32_e32 v55, v71, v225, vcc
	v_cmp_lt_i32_e32 vcc, v38, v16
	v_cmp_gt_i32_e64 s[10:11], v38, v17
	s_or_b64 vcc, vcc, s[10:11]
	v_or_b32_e32 v38, 0xa3, v18
	v_cndmask_b32_e32 v56, v72, v225, vcc
	v_cmp_lt_i32_e32 vcc, v38, v16
	v_cmp_gt_i32_e64 s[10:11], v38, v17
	s_or_b64 vcc, vcc, s[10:11]
	v_or_b32_e32 v38, 0xb0, v83
	v_cndmask_b32_e32 v57, v73, v225, vcc
	v_cmp_lt_i32_e32 vcc, v38, v16
	v_cmp_gt_i32_e64 s[10:11], v38, v17
	s_or_b64 vcc, vcc, s[10:11]
	v_or_b32_e32 v38, 0xb1, v83
	v_cndmask_b32_e32 v34, v34, v225, vcc
	v_cmp_lt_i32_e32 vcc, v38, v16
	v_cmp_gt_i32_e64 s[10:11], v38, v17
	s_or_b64 vcc, vcc, s[10:11]
	v_or_b32_e32 v38, 0xb2, v83
	v_cndmask_b32_e32 v35, v35, v225, vcc
	v_cmp_lt_i32_e32 vcc, v38, v16
	v_cmp_gt_i32_e64 s[10:11], v38, v17
	s_or_b64 vcc, vcc, s[10:11]
	v_cndmask_b32_e32 v62, v36, v225, vcc
	v_or_b32_e32 v36, 0xb3, v18
	v_cmp_lt_i32_e32 vcc, v36, v16
	v_cmp_gt_i32_e64 s[10:11], v36, v17
	s_or_b64 vcc, vcc, s[10:11]
	v_or_b32_e32 v36, 0xc0, v83
	v_cndmask_b32_e32 v64, v37, v225, vcc
	v_cmp_lt_i32_e32 vcc, v36, v16
	v_cmp_gt_i32_e64 s[10:11], v36, v17
	s_or_b64 vcc, vcc, s[10:11]
	v_or_b32_e32 v36, 0xc1, v83
	v_cndmask_b32_e32 v102, v74, v225, vcc
	v_cmp_lt_i32_e32 vcc, v36, v16
	v_cmp_gt_i32_e64 s[10:11], v36, v17
	s_or_b64 vcc, vcc, s[10:11]
	v_or_b32_e32 v36, 0xc2, v83
	v_cndmask_b32_e32 v103, v75, v225, vcc
	v_cmp_lt_i32_e32 vcc, v36, v16
	v_cmp_gt_i32_e64 s[10:11], v36, v17
	s_or_b64 vcc, vcc, s[10:11]
	v_or_b32_e32 v36, 0xc3, v18
	v_cndmask_b32_e32 v104, v76, v225, vcc
	v_cmp_lt_i32_e32 vcc, v36, v16
	v_cmp_gt_i32_e64 s[10:11], v36, v17
	s_or_b64 vcc, vcc, s[10:11]
	v_or_b32_e32 v36, 0xd0, v83
	v_cndmask_b32_e32 v105, v77, v225, vcc
	v_cmp_lt_i32_e32 vcc, v36, v16
	v_cmp_gt_i32_e64 s[10:11], v36, v17
	s_or_b64 vcc, vcc, s[10:11]
	v_or_b32_e32 v36, 0xd1, v83
	v_cndmask_b32_e32 v106, v66, v225, vcc
	v_cmp_lt_i32_e32 vcc, v36, v16
	v_cmp_gt_i32_e64 s[10:11], v36, v17
	s_or_b64 vcc, vcc, s[10:11]
	v_or_b32_e32 v36, 0xd2, v83
	v_cndmask_b32_e32 v107, v67, v225, vcc
	v_cmp_lt_i32_e32 vcc, v36, v16
	v_cmp_gt_i32_e64 s[10:11], v36, v17
	s_or_b64 vcc, vcc, s[10:11]
	v_or_b32_e32 v36, 0xd3, v18
	v_cndmask_b32_e32 v108, v68, v225, vcc
	v_cmp_lt_i32_e32 vcc, v36, v16
	v_cmp_gt_i32_e64 s[10:11], v36, v17
	s_or_b64 vcc, vcc, s[10:11]
	v_or_b32_e32 v36, 0xe0, v83
	v_cndmask_b32_e32 v109, v69, v225, vcc
	v_cmp_lt_i32_e32 vcc, v36, v16
	v_cmp_gt_i32_e64 s[10:11], v36, v17
	s_or_b64 vcc, vcc, s[10:11]
	v_or_b32_e32 v36, 0xe1, v83
	v_cndmask_b32_e32 v110, v78, v225, vcc
	v_cmp_lt_i32_e32 vcc, v36, v16
	v_cmp_gt_i32_e64 s[10:11], v36, v17
	s_or_b64 vcc, vcc, s[10:11]
	v_or_b32_e32 v36, 0xe2, v83
	v_cndmask_b32_e32 v111, v79, v225, vcc
	v_cmp_lt_i32_e32 vcc, v36, v16
	v_cmp_gt_i32_e64 s[10:11], v36, v17
	s_or_b64 vcc, vcc, s[10:11]
	v_or_b32_e32 v36, 0xe3, v18
	v_cndmask_b32_e32 v112, v80, v225, vcc
	v_cmp_lt_i32_e32 vcc, v36, v16
	v_cmp_gt_i32_e64 s[10:11], v36, v17
	s_or_b64 vcc, vcc, s[10:11]
	v_or_b32_e32 v36, 0xf0, v83
	v_cndmask_b32_e32 v113, v81, v225, vcc
	v_cmp_lt_i32_e32 vcc, v36, v16
	v_cmp_gt_i32_e64 s[10:11], v36, v17
	s_or_b64 vcc, vcc, s[10:11]
	v_or_b32_e32 v36, 0xf1, v83
	v_cndmask_b32_e32 v114, v50, v225, vcc
	v_cmp_lt_i32_e32 vcc, v36, v16
	v_cmp_gt_i32_e64 s[10:11], v36, v17
	s_or_b64 vcc, vcc, s[10:11]
	v_or_b32_e32 v36, 0xf2, v83
	v_cndmask_b32_e32 v115, v51, v225, vcc
	v_cmp_lt_i32_e32 vcc, v36, v16
	v_cmp_gt_i32_e64 s[10:11], v36, v17
	s_or_b64 vcc, vcc, s[10:11]
	v_or_b32_e32 v18, 0xf3, v18
	v_cndmask_b32_e32 v116, v52, v225, vcc
	v_cmp_lt_i32_e32 vcc, v18, v16
	v_cmp_gt_i32_e64 s[10:11], v18, v17
	v_max_f32_e32 v17, v12, v13
	v_max_f32_e32 v18, v14, v15
	s_mov_b32 s8, 0xff61b1e6
	v_max3_f32 v17, v17, v18, s8
	v_max_f32_e32 v18, v8, v9
	v_max_f32_e32 v36, v10, v11
	v_max3_f32 v17, v18, v36, v17
	v_max_f32_e32 v18, v19, v20
	v_max_f32_e32 v36, v21, v22
	v_max3_f32 v17, v18, v36, v17
	v_max_f32_e32 v18, v0, v1
	v_max_f32_e32 v36, v2, v3
	v_max3_f32 v17, v18, v36, v17
	v_max_f32_e32 v18, v23, v24
	v_max_f32_e32 v36, v25, v26
	v_max3_f32 v17, v18, v36, v17
	v_max_f32_e32 v18, v27, v28
	v_max_f32_e32 v36, v29, v30
	v_max3_f32 v17, v18, v36, v17
	v_max_f32_e32 v18, v31, v39
	v_max_f32_e32 v36, v40, v41
	v_max3_f32 v17, v18, v36, v17
	v_max_f32_e32 v18, v4, v5
	v_max_f32_e32 v36, v6, v7
	v_max3_f32 v17, v18, v36, v17
	v_max_f32_e32 v18, v42, v43
	v_max_f32_e32 v36, v44, v45
	v_max3_f32 v17, v18, v36, v17
	v_max_f32_e32 v18, v46, v47
	v_max_f32_e32 v36, v48, v49
	v_max3_f32 v17, v18, v36, v17
	v_max_f32_e32 v18, v54, v55
	v_max_f32_e32 v36, v56, v57
	v_max3_f32 v17, v18, v36, v17
	v_max_f32_e32 v18, v34, v35
	v_max_f32_e32 v36, v62, v64
	v_max3_f32 v17, v18, v36, v17
	v_max_f32_e32 v18, v102, v103
	v_max_f32_e32 v36, v104, v105
	v_max3_f32 v17, v18, v36, v17
	v_max_f32_e32 v18, v106, v107
	v_max_f32_e32 v36, v108, v109
	v_max3_f32 v17, v18, v36, v17
	v_max_f32_e32 v18, v110, v111
	s_or_b64 vcc, vcc, s[10:11]
	v_max_f32_e32 v36, v112, v113
	v_cndmask_b32_e32 v16, v53, v225, vcc
	v_max3_f32 v17, v18, v36, v17
	v_max_f32_e32 v18, v114, v115
	v_max_f32_e32 v36, v116, v16
	v_max3_f32 v17, v18, v36, v17
	ds_bpermute_b32 v18, v100, v17
	s_andn2_b64 vcc, exec, s[44:45]
	s_waitcnt lgkmcnt(0)
	v_max_f32_e32 v17, v17, v18
	ds_bpermute_b32 v18, v101, v17
	s_waitcnt lgkmcnt(0)
	v_max_f32_e32 v38, v17, v18
	v_sub_f32_e32 v12, v12, v38
	v_exp_f32_e32 v12, v12
	v_sub_f32_e32 v13, v13, v38
	v_exp_f32_e32 v13, v13
	v_sub_f32_e32 v14, v14, v38
	v_exp_f32_e32 v14, v14
	v_sub_f32_e32 v15, v15, v38
	v_exp_f32_e32 v15, v15
	v_sub_f32_e32 v8, v8, v38
	v_add_f32_e32 v17, 0, v12
	v_exp_f32_e32 v8, v8
	v_sub_f32_e32 v9, v9, v38
	v_add_f32_e32 v17, v13, v17
	v_exp_f32_e32 v9, v9
	v_sub_f32_e32 v10, v10, v38
	v_add_f32_e32 v17, v14, v17
	v_exp_f32_e32 v10, v10
	v_sub_f32_e32 v11, v11, v38
	v_add_f32_e32 v17, v15, v17
	v_exp_f32_e32 v11, v11
	v_sub_f32_e32 v18, v19, v38
	v_add_f32_e32 v17, v8, v17
	v_exp_f32_e32 v36, v18
	v_sub_f32_e32 v18, v20, v38
	v_add_f32_e32 v17, v9, v17
	v_exp_f32_e32 v37, v18
	v_sub_f32_e32 v18, v21, v38
	v_add_f32_e32 v17, v10, v17
	v_exp_f32_e32 v92, v18
	v_sub_f32_e32 v18, v22, v38
	v_add_f32_e32 v17, v11, v17
	v_exp_f32_e32 v93, v18
	v_sub_f32_e32 v0, v0, v38
	v_add_f32_e32 v17, v36, v17
	v_exp_f32_e32 v95, v0
	v_sub_f32_e32 v0, v1, v38
	v_add_f32_e32 v17, v37, v17
	v_exp_f32_e32 v97, v0
	v_sub_f32_e32 v0, v2, v38
	v_add_f32_e32 v17, v92, v17
	v_exp_f32_e32 v94, v0
	v_sub_f32_e32 v0, v3, v38
	v_add_f32_e32 v17, v93, v17
	v_exp_f32_e32 v96, v0
	v_sub_f32_e32 v1, v23, v38
	v_add_f32_e32 v0, v95, v17
	v_exp_f32_e32 v84, v1
	v_sub_f32_e32 v1, v24, v38
	v_add_f32_e32 v0, v97, v0
	v_exp_f32_e32 v85, v1
	v_sub_f32_e32 v1, v25, v38
	v_add_f32_e32 v0, v94, v0
	v_exp_f32_e32 v86, v1
	v_sub_f32_e32 v1, v26, v38
	v_add_f32_e32 v0, v96, v0
	v_exp_f32_e32 v87, v1
	v_sub_f32_e32 v1, v27, v38
	v_add_f32_e32 v0, v84, v0
	v_exp_f32_e32 v89, v1
	v_sub_f32_e32 v1, v28, v38
	v_add_f32_e32 v0, v85, v0
	v_exp_f32_e32 v91, v1
	v_sub_f32_e32 v1, v29, v38
	v_add_f32_e32 v0, v86, v0
	v_exp_f32_e32 v88, v1
	v_sub_f32_e32 v1, v30, v38
	v_add_f32_e32 v0, v87, v0
	v_exp_f32_e32 v90, v1
	v_sub_f32_e32 v1, v31, v38
	v_add_f32_e32 v0, v89, v0
	v_exp_f32_e32 v74, v1
	v_sub_f32_e32 v1, v39, v38
	v_add_f32_e32 v0, v91, v0
	v_exp_f32_e32 v75, v1
	v_sub_f32_e32 v1, v40, v38
	v_add_f32_e32 v0, v88, v0
	v_exp_f32_e32 v76, v1
	v_sub_f32_e32 v1, v41, v38
	v_add_f32_e32 v0, v90, v0
	v_exp_f32_e32 v77, v1
	v_sub_f32_e32 v1, v4, v38
	v_add_f32_e32 v0, v74, v0
	v_exp_f32_e32 v79, v1
	v_sub_f32_e32 v1, v5, v38
	v_add_f32_e32 v0, v75, v0
	v_exp_f32_e32 v81, v1
	v_sub_f32_e32 v1, v6, v38
	v_add_f32_e32 v0, v76, v0
	v_exp_f32_e32 v78, v1
	v_sub_f32_e32 v1, v7, v38
	v_add_f32_e32 v0, v77, v0
	v_exp_f32_e32 v80, v1
	v_sub_f32_e32 v1, v42, v38
	v_add_f32_e32 v0, v79, v0
	v_exp_f32_e32 v66, v1
	v_sub_f32_e32 v1, v43, v38
	v_add_f32_e32 v0, v81, v0
	v_exp_f32_e32 v67, v1
	v_sub_f32_e32 v1, v44, v38
	v_add_f32_e32 v0, v78, v0
	v_exp_f32_e32 v68, v1
	v_sub_f32_e32 v1, v45, v38
	v_add_f32_e32 v0, v80, v0
	v_exp_f32_e32 v69, v1
	v_sub_f32_e32 v1, v46, v38
	v_add_f32_e32 v0, v66, v0
	v_exp_f32_e32 v71, v1
	v_sub_f32_e32 v1, v47, v38
	v_add_f32_e32 v0, v67, v0
	v_exp_f32_e32 v73, v1
	v_sub_f32_e32 v1, v48, v38
	v_add_f32_e32 v0, v68, v0
	v_exp_f32_e32 v70, v1
	v_sub_f32_e32 v1, v49, v38
	v_add_f32_e32 v0, v69, v0
	v_exp_f32_e32 v72, v1
	v_sub_f32_e32 v1, v54, v38
	v_add_f32_e32 v0, v71, v0
	v_exp_f32_e32 v58, v1
	v_sub_f32_e32 v1, v55, v38
	v_add_f32_e32 v0, v73, v0
	v_exp_f32_e32 v59, v1
	v_sub_f32_e32 v1, v56, v38
	v_add_f32_e32 v0, v70, v0
	v_exp_f32_e32 v60, v1
	v_sub_f32_e32 v1, v57, v38
	v_add_f32_e32 v0, v72, v0
	v_exp_f32_e32 v61, v1
	v_sub_f32_e32 v1, v34, v38
	v_add_f32_e32 v0, v58, v0
	v_exp_f32_e32 v63, v1
	v_sub_f32_e32 v1, v35, v38
	v_add_f32_e32 v0, v59, v0
	v_exp_f32_e32 v65, v1
	v_sub_f32_e32 v1, v62, v38
	v_add_f32_e32 v0, v60, v0
	v_exp_f32_e32 v62, v1
	v_sub_f32_e32 v1, v64, v38
	v_add_f32_e32 v0, v61, v0
	v_exp_f32_e32 v64, v1
	v_sub_f32_e32 v1, v102, v38
	v_add_f32_e32 v0, v63, v0
	v_exp_f32_e32 v50, v1
	v_sub_f32_e32 v1, v103, v38
	v_add_f32_e32 v0, v65, v0
	v_exp_f32_e32 v51, v1
	v_sub_f32_e32 v1, v104, v38
	v_add_f32_e32 v0, v62, v0
	v_exp_f32_e32 v52, v1
	v_sub_f32_e32 v1, v105, v38
	v_add_f32_e32 v0, v64, v0
	v_exp_f32_e32 v53, v1
	v_sub_f32_e32 v1, v106, v38
	v_add_f32_e32 v0, v50, v0
	v_exp_f32_e32 v55, v1
	v_sub_f32_e32 v1, v107, v38
	v_add_f32_e32 v0, v51, v0
	v_exp_f32_e32 v57, v1
	v_sub_f32_e32 v1, v108, v38
	v_add_f32_e32 v0, v52, v0
	v_exp_f32_e32 v54, v1
	v_sub_f32_e32 v1, v109, v38
	v_add_f32_e32 v0, v53, v0
	v_exp_f32_e32 v56, v1
	v_sub_f32_e32 v1, v110, v38
	v_add_f32_e32 v0, v55, v0
	v_exp_f32_e32 v42, v1
	v_sub_f32_e32 v1, v111, v38
	v_add_f32_e32 v0, v57, v0
	v_exp_f32_e32 v43, v1
	v_sub_f32_e32 v1, v112, v38
	v_add_f32_e32 v0, v54, v0
	v_exp_f32_e32 v44, v1
	v_sub_f32_e32 v1, v113, v38
	v_add_f32_e32 v0, v56, v0
	v_exp_f32_e32 v45, v1
	v_sub_f32_e32 v1, v114, v38
	v_add_f32_e32 v0, v42, v0
	v_exp_f32_e32 v47, v1
	v_sub_f32_e32 v1, v115, v38
	v_add_f32_e32 v0, v43, v0
	v_exp_f32_e32 v49, v1
	v_sub_f32_e32 v1, v116, v38
	v_add_f32_e32 v0, v44, v0
	v_exp_f32_e32 v46, v1
	v_sub_f32_e32 v1, v16, v38
	v_add_f32_e32 v0, v45, v0
	v_exp_f32_e32 v48, v1
	v_add_f32_e32 v0, v47, v0
	v_add_f32_e32 v0, v49, v0
	v_add_f32_e32 v0, v46, v0
	v_add_f32_e32 v0, v48, v0
	ds_bpermute_b32 v1, v100, v0
	v_cvt_pk_bf16_f32 v2, v8, v9
	v_cvt_pk_bf16_f32 v3, v10, v11
	s_waitcnt lgkmcnt(0)
	v_add_f32_e32 v39, v0, v1
	ds_bpermute_b32 v40, v101, v39
	v_lshrrev_b32_e32 v0, 2, v32
	v_or_b32_e32 v0, v83, v0
	v_lshlrev_b32_e32 v1, 3, v98
	v_mul_u32_u24_e32 v0, 0x120, v0
	v_and_b32_e32 v1, 24, v1
	v_add3_u32 v41, s27, v0, v1
	v_cvt_pk_bf16_f32 v0, v12, v13
	v_cvt_pk_bf16_f32 v1, v14, v15
	s_cbranch_vccnz .LBB0_1295
	ds_read_b64_tr_b16 v[4:5], v41
	ds_read_b64_tr_b16 v[8:9], v41 offset:32
	ds_read_b64_tr_b16 v[12:13], v41 offset:64
	ds_read_b64_tr_b16 v[16:17], v41 offset:96
	ds_read_b64_tr_b16 v[6:7], v41 offset:4608
	ds_read_b64_tr_b16 v[10:11], v41 offset:4640
	ds_read_b64_tr_b16 v[14:15], v41 offset:4672
	ds_read_b64_tr_b16 v[18:19], v41 offset:4704
	ds_read_b64_tr_b16 v[102:103], v41 offset:128
	ds_read_b64_tr_b16 v[106:107], v41 offset:160
	ds_read_b64_tr_b16 v[110:111], v41 offset:192
	ds_read_b64_tr_b16 v[114:115], v41 offset:224
	ds_read_b64_tr_b16 v[104:105], v41 offset:4736
	ds_read_b64_tr_b16 v[108:109], v41 offset:4768
	ds_read_b64_tr_b16 v[112:113], v41 offset:4800
	ds_read_b64_tr_b16 v[116:117], v41 offset:4832
	s_waitcnt lgkmcnt(11)
	v_mfma_f32_16x16x32_bf16 v[28:31], v[4:7], v[0:3], 0
	s_waitcnt lgkmcnt(10)
	v_mfma_f32_16x16x32_bf16 v[24:27], v[8:11], v[0:3], 0
	s_waitcnt lgkmcnt(9)
	v_mfma_f32_16x16x32_bf16 v[20:23], v[12:15], v[0:3], 0
	s_waitcnt lgkmcnt(8)
	v_mfma_f32_16x16x32_bf16 v[16:19], v[16:19], v[0:3], 0
	s_waitcnt lgkmcnt(3)
	v_mfma_f32_16x16x32_bf16 v[12:15], v[102:105], v[0:3], 0
	s_waitcnt lgkmcnt(2)
	v_mfma_f32_16x16x32_bf16 v[8:11], v[106:109], v[0:3], 0
	s_waitcnt lgkmcnt(1)
	v_mfma_f32_16x16x32_bf16 v[4:7], v[110:113], v[0:3], 0
	s_waitcnt lgkmcnt(0)
	v_mfma_f32_16x16x32_bf16 v[0:3], v[114:117], v[0:3], 0
	s_branch .LBB0_1296

.LBB0_1331:
	v_lshl_or_b32 v82, s73, 4, v32
	v_readlane_b32 s8, v252, 61
	s_nop 0
	v_max_i32_e32 v16, 0x80, v82
	v_readlane_b32 s9, v252, 62
	v_lshrrev_b32_e32 v18, 2, v98
	v_add_u32_e32 v17, 0x80, v82
	v_cndmask_b32_e64 v16, v82, v16, s[8:9]
	v_and_b32_e32 v83, 12, v18
	v_cmp_lt_i32_e32 vcc, v83, v16
	v_cmp_gt_i32_e64 s[10:11], v83, v17
	s_or_b64 vcc, vcc, s[10:11]
	v_or_b32_e32 v19, 1, v83
	v_cndmask_b32_e32 v12, v12, v225, vcc
	v_cmp_lt_i32_e32 vcc, v19, v16
	v_cmp_ge_i32_e64 s[10:11], v83, v17
	s_or_b64 vcc, vcc, s[10:11]
	v_or_b32_e32 v19, 2, v83
	v_cndmask_b32_e32 v13, v13, v225, vcc
	v_cmp_lt_i32_e32 vcc, v19, v16
	v_cmp_gt_i32_e64 s[10:11], v19, v17
	s_or_b64 vcc, vcc, s[10:11]
	v_or_b32_e32 v19, 3, v18
	v_cndmask_b32_e32 v14, v14, v225, vcc
	v_cmp_lt_i32_e32 vcc, v19, v16
	v_cmp_gt_i32_e64 s[10:11], v19, v17
	s_or_b64 vcc, vcc, s[10:11]
	v_or_b32_e32 v19, 16, v83
	v_cndmask_b32_e32 v15, v15, v225, vcc
	v_cmp_lt_i32_e32 vcc, v19, v16
	v_cmp_gt_i32_e64 s[10:11], v19, v17
	s_or_b64 vcc, vcc, s[10:11]
	v_or_b32_e32 v19, 17, v83
	v_cndmask_b32_e32 v8, v8, v225, vcc
	v_cmp_lt_i32_e32 vcc, v19, v16
	v_cmp_gt_i32_e64 s[10:11], v19, v17
	s_or_b64 vcc, vcc, s[10:11]
	v_or_b32_e32 v19, 18, v83
	v_cndmask_b32_e32 v9, v9, v225, vcc
	v_cmp_lt_i32_e32 vcc, v19, v16
	v_cmp_gt_i32_e64 s[10:11], v19, v17
	s_or_b64 vcc, vcc, s[10:11]
	v_or_b32_e32 v19, 19, v18
	v_cndmask_b32_e32 v10, v10, v225, vcc
	v_cmp_lt_i32_e32 vcc, v19, v16
	v_cmp_gt_i32_e64 s[10:11], v19, v17
	s_or_b64 vcc, vcc, s[10:11]
	v_or_b32_e32 v19, 32, v83
	v_cndmask_b32_e32 v11, v11, v225, vcc
	v_cmp_lt_i32_e32 vcc, v19, v16
	v_cmp_gt_i32_e64 s[10:11], v19, v17
	s_or_b64 vcc, vcc, s[10:11]
	v_or_b32_e32 v20, 33, v83
	v_cndmask_b32_e32 v19, v42, v225, vcc
	v_cmp_lt_i32_e32 vcc, v20, v16
	v_cmp_gt_i32_e64 s[10:11], v20, v17
	s_or_b64 vcc, vcc, s[10:11]
	v_or_b32_e32 v21, 34, v83
	v_cndmask_b32_e32 v20, v43, v225, vcc
	v_cmp_lt_i32_e32 vcc, v21, v16
	v_cmp_gt_i32_e64 s[10:11], v21, v17
	s_or_b64 vcc, vcc, s[10:11]
	v_or_b32_e32 v22, 35, v18
	v_cndmask_b32_e32 v21, v44, v225, vcc
	v_cmp_lt_i32_e32 vcc, v22, v16
	v_cmp_gt_i32_e64 s[10:11], v22, v17
	s_or_b64 vcc, vcc, s[10:11]
	v_or_b32_e32 v23, 48, v83
	v_cndmask_b32_e32 v22, v45, v225, vcc
	v_cmp_lt_i32_e32 vcc, v23, v16
	v_cmp_gt_i32_e64 s[10:11], v23, v17
	s_or_b64 vcc, vcc, s[10:11]
	v_or_b32_e32 v23, 49, v83
	v_cndmask_b32_e32 v0, v0, v225, vcc
	v_cmp_lt_i32_e32 vcc, v23, v16
	v_cmp_gt_i32_e64 s[10:11], v23, v17
	s_or_b64 vcc, vcc, s[10:11]
	v_or_b32_e32 v23, 50, v83
	v_cndmask_b32_e32 v1, v1, v225, vcc
	v_cmp_lt_i32_e32 vcc, v23, v16
	v_cmp_gt_i32_e64 s[10:11], v23, v17
	s_or_b64 vcc, vcc, s[10:11]
	v_or_b32_e32 v23, 51, v18
	v_cndmask_b32_e32 v2, v2, v225, vcc
	v_cmp_lt_i32_e32 vcc, v23, v16
	v_cmp_gt_i32_e64 s[10:11], v23, v17
	s_or_b64 vcc, vcc, s[10:11]
	v_or_b32_e32 v23, 64, v83
	v_cndmask_b32_e32 v3, v3, v225, vcc
	v_cmp_lt_i32_e32 vcc, v23, v16
	v_cmp_gt_i32_e64 s[10:11], v23, v17
	s_or_b64 vcc, vcc, s[10:11]
	v_or_b32_e32 v24, 0x41, v83
	v_cndmask_b32_e32 v23, v46, v225, vcc
	v_cmp_lt_i32_e32 vcc, v24, v16
	v_cmp_gt_i32_e64 s[10:11], v24, v17
	s_or_b64 vcc, vcc, s[10:11]
	v_or_b32_e32 v25, 0x42, v83
	v_cndmask_b32_e32 v24, v47, v225, vcc
	v_cmp_lt_i32_e32 vcc, v25, v16
	v_cmp_gt_i32_e64 s[10:11], v25, v17
	s_or_b64 vcc, vcc, s[10:11]
	v_or_b32_e32 v26, 0x43, v18
	v_cndmask_b32_e32 v25, v48, v225, vcc
	v_cmp_lt_i32_e32 vcc, v26, v16
	v_cmp_gt_i32_e64 s[10:11], v26, v17
	s_or_b64 vcc, vcc, s[10:11]
	v_or_b32_e32 v27, 0x50, v83
	v_cndmask_b32_e32 v26, v49, v225, vcc
	v_cmp_lt_i32_e32 vcc, v27, v16
	v_cmp_gt_i32_e64 s[10:11], v27, v17
	s_or_b64 vcc, vcc, s[10:11]
	v_or_b32_e32 v28, 0x51, v83
	v_cndmask_b32_e32 v27, v38, v225, vcc
	v_cmp_lt_i32_e32 vcc, v28, v16
	v_cmp_gt_i32_e64 s[10:11], v28, v17
	s_or_b64 vcc, vcc, s[10:11]
	v_or_b32_e32 v29, 0x52, v83
	v_cndmask_b32_e32 v28, v39, v225, vcc
	v_cmp_lt_i32_e32 vcc, v29, v16
	v_cmp_gt_i32_e64 s[10:11], v29, v17
	s_or_b64 vcc, vcc, s[10:11]
	v_or_b32_e32 v30, 0x53, v18
	v_cndmask_b32_e32 v29, v40, v225, vcc
	v_cmp_lt_i32_e32 vcc, v30, v16
	v_cmp_gt_i32_e64 s[10:11], v30, v17
	s_or_b64 vcc, vcc, s[10:11]
	v_or_b32_e32 v31, 0x60, v83
	v_cndmask_b32_e32 v30, v41, v225, vcc
	v_cmp_lt_i32_e32 vcc, v31, v16
	v_cmp_gt_i32_e64 s[10:11], v31, v17
	s_or_b64 vcc, vcc, s[10:11]
	v_or_b32_e32 v38, 0x61, v83
	v_cndmask_b32_e32 v31, v58, v225, vcc
	v_cmp_lt_i32_e32 vcc, v38, v16
	v_cmp_gt_i32_e64 s[10:11], v38, v17
	s_or_b64 vcc, vcc, s[10:11]
	v_or_b32_e32 v38, 0x62, v83
	v_cndmask_b32_e32 v39, v59, v225, vcc
	v_cmp_lt_i32_e32 vcc, v38, v16
	v_cmp_gt_i32_e64 s[10:11], v38, v17
	s_or_b64 vcc, vcc, s[10:11]
	v_or_b32_e32 v38, 0x63, v18
	v_cndmask_b32_e32 v40, v60, v225, vcc
	v_cmp_lt_i32_e32 vcc, v38, v16
	v_cmp_gt_i32_e64 s[10:11], v38, v17
	s_or_b64 vcc, vcc, s[10:11]
	v_or_b32_e32 v38, 0x70, v83
	v_cndmask_b32_e32 v41, v61, v225, vcc
	v_cmp_lt_i32_e32 vcc, v38, v16
	v_cmp_gt_i32_e64 s[10:11], v38, v17
	s_or_b64 vcc, vcc, s[10:11]
	v_or_b32_e32 v38, 0x71, v83
	v_cndmask_b32_e32 v4, v4, v225, vcc
	v_cmp_lt_i32_e32 vcc, v38, v16
	v_cmp_gt_i32_e64 s[10:11], v38, v17
	s_or_b64 vcc, vcc, s[10:11]
	v_or_b32_e32 v38, 0x72, v83
	v_cndmask_b32_e32 v5, v5, v225, vcc
	v_cmp_lt_i32_e32 vcc, v38, v16
	v_cmp_gt_i32_e64 s[10:11], v38, v17
	s_or_b64 vcc, vcc, s[10:11]
	v_or_b32_e32 v38, 0x73, v18
	v_cndmask_b32_e32 v6, v6, v225, vcc
	v_cmp_lt_i32_e32 vcc, v38, v16
	v_cmp_gt_i32_e64 s[10:11], v38, v17
	s_or_b64 vcc, vcc, s[10:11]
	v_or_b32_e32 v38, 0x80, v83
	v_cndmask_b32_e32 v7, v7, v225, vcc
	v_cmp_lt_i32_e32 vcc, v38, v16
	v_cmp_gt_i32_e64 s[10:11], v83, v82
	s_or_b64 vcc, vcc, s[10:11]
	v_or_b32_e32 v38, 0x81, v83
	v_cndmask_b32_e32 v42, v62, v225, vcc
	v_cmp_lt_i32_e32 vcc, v38, v16
	v_cmp_gt_i32_e64 s[10:11], v38, v17
	s_or_b64 vcc, vcc, s[10:11]
	v_or_b32_e32 v38, 0x82, v83
	v_cndmask_b32_e32 v43, v63, v225, vcc
	v_cmp_lt_i32_e32 vcc, v38, v16
	v_cmp_gt_i32_e64 s[10:11], v38, v17
	s_or_b64 vcc, vcc, s[10:11]
	v_or_b32_e32 v38, 0x83, v18
	v_cndmask_b32_e32 v44, v64, v225, vcc
	v_cmp_lt_i32_e32 vcc, v38, v16
	v_cmp_gt_i32_e64 s[10:11], v38, v17
	s_or_b64 vcc, vcc, s[10:11]
	v_or_b32_e32 v38, 0x90, v83
	v_cndmask_b32_e32 v45, v65, v225, vcc
	v_cmp_lt_i32_e32 vcc, v38, v16
	v_cmp_gt_i32_e64 s[10:11], v38, v17
	s_or_b64 vcc, vcc, s[10:11]
	v_or_b32_e32 v38, 0x91, v83
	v_cndmask_b32_e32 v46, v54, v225, vcc
	v_cmp_lt_i32_e32 vcc, v38, v16
	v_cmp_gt_i32_e64 s[10:11], v38, v17
	s_or_b64 vcc, vcc, s[10:11]
	v_or_b32_e32 v38, 0x92, v83
	v_cndmask_b32_e32 v47, v55, v225, vcc
	v_cmp_lt_i32_e32 vcc, v38, v16
	v_cmp_gt_i32_e64 s[10:11], v38, v17
	s_or_b64 vcc, vcc, s[10:11]
	v_or_b32_e32 v38, 0x93, v18
	v_cndmask_b32_e32 v48, v56, v225, vcc
	v_cmp_lt_i32_e32 vcc, v38, v16
	v_cmp_gt_i32_e64 s[10:11], v38, v17
	s_or_b64 vcc, vcc, s[10:11]
	v_or_b32_e32 v38, 0xa0, v83
	v_cndmask_b32_e32 v49, v57, v225, vcc
	v_cmp_lt_i32_e32 vcc, v38, v16
	v_cmp_gt_i32_e64 s[10:11], v38, v17
	s_or_b64 vcc, vcc, s[10:11]
	v_or_b32_e32 v38, 0xa1, v83
	v_cndmask_b32_e32 v54, v70, v225, vcc
	v_cmp_lt_i32_e32 vcc, v38, v16
	v_cmp_gt_i32_e64 s[10:11], v38, v17
	s_or_b64 vcc, vcc, s[10:11]
	v_or_b32_e32 v38, 0xa2, v83
	v_cndmask_b32_e32 v55, v71, v225, vcc
	v_cmp_lt_i32_e32 vcc, v38, v16
	v_cmp_gt_i32_e64 s[10:11], v38, v17
	s_or_b64 vcc, vcc, s[10:11]
	v_or_b32_e32 v38, 0xa3, v18
	v_cndmask_b32_e32 v56, v72, v225, vcc
	v_cmp_lt_i32_e32 vcc, v38, v16
	v_cmp_gt_i32_e64 s[10:11], v38, v17
	s_or_b64 vcc, vcc, s[10:11]
	v_or_b32_e32 v38, 0xb0, v83
	v_cndmask_b32_e32 v57, v73, v225, vcc
	v_cmp_lt_i32_e32 vcc, v38, v16
	v_cmp_gt_i32_e64 s[10:11], v38, v17
	s_or_b64 vcc, vcc, s[10:11]
	v_or_b32_e32 v38, 0xb1, v83
	v_cndmask_b32_e32 v34, v34, v225, vcc
	v_cmp_lt_i32_e32 vcc, v38, v16
	v_cmp_gt_i32_e64 s[10:11], v38, v17
	s_or_b64 vcc, vcc, s[10:11]
	v_or_b32_e32 v38, 0xb2, v83
	v_cndmask_b32_e32 v35, v35, v225, vcc
	v_cmp_lt_i32_e32 vcc, v38, v16
	v_cmp_gt_i32_e64 s[10:11], v38, v17
	s_or_b64 vcc, vcc, s[10:11]
	v_cndmask_b32_e32 v62, v36, v225, vcc
	v_or_b32_e32 v36, 0xb3, v18
	v_cmp_lt_i32_e32 vcc, v36, v16
	v_cmp_gt_i32_e64 s[10:11], v36, v17
	s_or_b64 vcc, vcc, s[10:11]
	v_or_b32_e32 v36, 0xc0, v83
	v_cndmask_b32_e32 v64, v37, v225, vcc
	v_cmp_lt_i32_e32 vcc, v36, v16
	v_cmp_gt_i32_e64 s[10:11], v36, v17
	s_or_b64 vcc, vcc, s[10:11]
	v_or_b32_e32 v36, 0xc1, v83
	v_cndmask_b32_e32 v102, v74, v225, vcc
	v_cmp_lt_i32_e32 vcc, v36, v16
	v_cmp_gt_i32_e64 s[10:11], v36, v17
	s_or_b64 vcc, vcc, s[10:11]
	v_or_b32_e32 v36, 0xc2, v83
	v_cndmask_b32_e32 v103, v75, v225, vcc
	v_cmp_lt_i32_e32 vcc, v36, v16
	v_cmp_gt_i32_e64 s[10:11], v36, v17
	s_or_b64 vcc, vcc, s[10:11]
	v_or_b32_e32 v36, 0xc3, v18
	v_cndmask_b32_e32 v104, v76, v225, vcc
	v_cmp_lt_i32_e32 vcc, v36, v16
	v_cmp_gt_i32_e64 s[10:11], v36, v17
	s_or_b64 vcc, vcc, s[10:11]
	v_or_b32_e32 v36, 0xd0, v83
	v_cndmask_b32_e32 v105, v77, v225, vcc
	v_cmp_lt_i32_e32 vcc, v36, v16
	v_cmp_gt_i32_e64 s[10:11], v36, v17
	s_or_b64 vcc, vcc, s[10:11]
	v_or_b32_e32 v36, 0xd1, v83
	v_cndmask_b32_e32 v106, v66, v225, vcc
	v_cmp_lt_i32_e32 vcc, v36, v16
	v_cmp_gt_i32_e64 s[10:11], v36, v17
	s_or_b64 vcc, vcc, s[10:11]
	v_or_b32_e32 v36, 0xd2, v83
	v_cndmask_b32_e32 v107, v67, v225, vcc
	v_cmp_lt_i32_e32 vcc, v36, v16
	v_cmp_gt_i32_e64 s[10:11], v36, v17
	s_or_b64 vcc, vcc, s[10:11]
	v_or_b32_e32 v36, 0xd3, v18
	v_cndmask_b32_e32 v108, v68, v225, vcc
	v_cmp_lt_i32_e32 vcc, v36, v16
	v_cmp_gt_i32_e64 s[10:11], v36, v17
	s_or_b64 vcc, vcc, s[10:11]
	v_or_b32_e32 v36, 0xe0, v83
	v_cndmask_b32_e32 v109, v69, v225, vcc
	v_cmp_lt_i32_e32 vcc, v36, v16
	v_cmp_gt_i32_e64 s[10:11], v36, v17
	s_or_b64 vcc, vcc, s[10:11]
	v_or_b32_e32 v36, 0xe1, v83
	v_cndmask_b32_e32 v110, v78, v225, vcc
	v_cmp_lt_i32_e32 vcc, v36, v16
	v_cmp_gt_i32_e64 s[10:11], v36, v17
	s_or_b64 vcc, vcc, s[10:11]
	v_or_b32_e32 v36, 0xe2, v83
	v_cndmask_b32_e32 v111, v79, v225, vcc
	v_cmp_lt_i32_e32 vcc, v36, v16
	v_cmp_gt_i32_e64 s[10:11], v36, v17
	s_or_b64 vcc, vcc, s[10:11]
	v_or_b32_e32 v36, 0xe3, v18
	v_cndmask_b32_e32 v112, v80, v225, vcc
	v_cmp_lt_i32_e32 vcc, v36, v16
	v_cmp_gt_i32_e64 s[10:11], v36, v17
	s_or_b64 vcc, vcc, s[10:11]
	v_or_b32_e32 v36, 0xf0, v83
	v_cndmask_b32_e32 v113, v81, v225, vcc
	v_cmp_lt_i32_e32 vcc, v36, v16
	v_cmp_gt_i32_e64 s[10:11], v36, v17
	s_or_b64 vcc, vcc, s[10:11]
	v_or_b32_e32 v36, 0xf1, v83
	v_cndmask_b32_e32 v114, v50, v225, vcc
	v_cmp_lt_i32_e32 vcc, v36, v16
	v_cmp_gt_i32_e64 s[10:11], v36, v17
	s_or_b64 vcc, vcc, s[10:11]
	v_or_b32_e32 v36, 0xf2, v83
	v_cndmask_b32_e32 v115, v51, v225, vcc
	v_cmp_lt_i32_e32 vcc, v36, v16
	v_cmp_gt_i32_e64 s[10:11], v36, v17
	s_or_b64 vcc, vcc, s[10:11]
	v_or_b32_e32 v18, 0xf3, v18
	v_cndmask_b32_e32 v116, v52, v225, vcc
	v_cmp_lt_i32_e32 vcc, v18, v16
	v_cmp_gt_i32_e64 s[10:11], v18, v17
	v_max_f32_e32 v17, v12, v13
	v_max_f32_e32 v18, v14, v15
	s_mov_b32 s8, 0xff61b1e6
	v_max3_f32 v17, v17, v18, s8
	v_max_f32_e32 v18, v8, v9
	v_max_f32_e32 v36, v10, v11
	v_max3_f32 v17, v18, v36, v17
	v_max_f32_e32 v18, v19, v20
	v_max_f32_e32 v36, v21, v22
	v_max3_f32 v17, v18, v36, v17
	v_max_f32_e32 v18, v0, v1
	v_max_f32_e32 v36, v2, v3
	v_max3_f32 v17, v18, v36, v17
	v_max_f32_e32 v18, v23, v24
	v_max_f32_e32 v36, v25, v26
	v_max3_f32 v17, v18, v36, v17
	v_max_f32_e32 v18, v27, v28
	v_max_f32_e32 v36, v29, v30
	v_max3_f32 v17, v18, v36, v17
	v_max_f32_e32 v18, v31, v39
	v_max_f32_e32 v36, v40, v41
	v_max3_f32 v17, v18, v36, v17
	v_max_f32_e32 v18, v4, v5
	v_max_f32_e32 v36, v6, v7
	v_max3_f32 v17, v18, v36, v17
	v_max_f32_e32 v18, v42, v43
	v_max_f32_e32 v36, v44, v45
	v_max3_f32 v17, v18, v36, v17
	v_max_f32_e32 v18, v46, v47
	v_max_f32_e32 v36, v48, v49
	v_max3_f32 v17, v18, v36, v17
	v_max_f32_e32 v18, v54, v55
	v_max_f32_e32 v36, v56, v57
	v_max3_f32 v17, v18, v36, v17
	v_max_f32_e32 v18, v34, v35
	v_max_f32_e32 v36, v62, v64
	v_max3_f32 v17, v18, v36, v17
	v_max_f32_e32 v18, v102, v103
	v_max_f32_e32 v36, v104, v105
	v_max3_f32 v17, v18, v36, v17
	v_max_f32_e32 v18, v106, v107
	v_max_f32_e32 v36, v108, v109
	v_max3_f32 v17, v18, v36, v17
	v_max_f32_e32 v18, v110, v111
	s_or_b64 vcc, vcc, s[10:11]
	v_max_f32_e32 v36, v112, v113
	v_cndmask_b32_e32 v16, v53, v225, vcc
	v_max3_f32 v17, v18, v36, v17
	v_max_f32_e32 v18, v114, v115
	v_max_f32_e32 v36, v116, v16
	v_max3_f32 v17, v18, v36, v17
	ds_bpermute_b32 v18, v100, v17
	s_andn2_b64 vcc, exec, s[44:45]
	s_waitcnt lgkmcnt(0)
	v_max_f32_e32 v17, v17, v18
	ds_bpermute_b32 v18, v101, v17
	s_waitcnt lgkmcnt(0)
	v_max_f32_e32 v38, v17, v18
	v_sub_f32_e32 v12, v12, v38
	v_exp_f32_e32 v12, v12
	v_sub_f32_e32 v13, v13, v38
	v_exp_f32_e32 v13, v13
	v_sub_f32_e32 v14, v14, v38
	v_exp_f32_e32 v14, v14
	v_sub_f32_e32 v15, v15, v38
	v_exp_f32_e32 v15, v15
	v_sub_f32_e32 v8, v8, v38
	v_add_f32_e32 v17, 0, v12
	v_exp_f32_e32 v8, v8
	v_sub_f32_e32 v9, v9, v38
	v_add_f32_e32 v17, v13, v17
	v_exp_f32_e32 v9, v9
	v_sub_f32_e32 v10, v10, v38
	v_add_f32_e32 v17, v14, v17
	v_exp_f32_e32 v10, v10
	v_sub_f32_e32 v11, v11, v38
	v_add_f32_e32 v17, v15, v17
	v_exp_f32_e32 v11, v11
	v_sub_f32_e32 v18, v19, v38
	v_add_f32_e32 v17, v8, v17
	v_exp_f32_e32 v36, v18
	v_sub_f32_e32 v18, v20, v38
	v_add_f32_e32 v17, v9, v17
	v_exp_f32_e32 v37, v18
	v_sub_f32_e32 v18, v21, v38
	v_add_f32_e32 v17, v10, v17
	v_exp_f32_e32 v92, v18
	v_sub_f32_e32 v18, v22, v38
	v_add_f32_e32 v17, v11, v17
	v_exp_f32_e32 v93, v18
	v_sub_f32_e32 v0, v0, v38
	v_add_f32_e32 v17, v36, v17
	v_exp_f32_e32 v95, v0
	v_sub_f32_e32 v0, v1, v38
	v_add_f32_e32 v17, v37, v17
	v_exp_f32_e32 v97, v0
	v_sub_f32_e32 v0, v2, v38
	v_add_f32_e32 v17, v92, v17
	v_exp_f32_e32 v94, v0
	v_sub_f32_e32 v0, v3, v38
	v_add_f32_e32 v17, v93, v17
	v_exp_f32_e32 v96, v0
	v_sub_f32_e32 v1, v23, v38
	v_add_f32_e32 v0, v95, v17
	v_exp_f32_e32 v84, v1
	v_sub_f32_e32 v1, v24, v38
	v_add_f32_e32 v0, v97, v0
	v_exp_f32_e32 v85, v1
	v_sub_f32_e32 v1, v25, v38
	v_add_f32_e32 v0, v94, v0
	v_exp_f32_e32 v86, v1
	v_sub_f32_e32 v1, v26, v38
	v_add_f32_e32 v0, v96, v0
	v_exp_f32_e32 v87, v1
	v_sub_f32_e32 v1, v27, v38
	v_add_f32_e32 v0, v84, v0
	v_exp_f32_e32 v89, v1
	v_sub_f32_e32 v1, v28, v38
	v_add_f32_e32 v0, v85, v0
	v_exp_f32_e32 v91, v1
	v_sub_f32_e32 v1, v29, v38
	v_add_f32_e32 v0, v86, v0
	v_exp_f32_e32 v88, v1
	v_sub_f32_e32 v1, v30, v38
	v_add_f32_e32 v0, v87, v0
	v_exp_f32_e32 v90, v1
	v_sub_f32_e32 v1, v31, v38
	v_add_f32_e32 v0, v89, v0
	v_exp_f32_e32 v74, v1
	v_sub_f32_e32 v1, v39, v38
	v_add_f32_e32 v0, v91, v0
	v_exp_f32_e32 v75, v1
	v_sub_f32_e32 v1, v40, v38
	v_add_f32_e32 v0, v88, v0
	v_exp_f32_e32 v76, v1
	v_sub_f32_e32 v1, v41, v38
	v_add_f32_e32 v0, v90, v0
	v_exp_f32_e32 v77, v1
	v_sub_f32_e32 v1, v4, v38
	v_add_f32_e32 v0, v74, v0
	v_exp_f32_e32 v79, v1
	v_sub_f32_e32 v1, v5, v38
	v_add_f32_e32 v0, v75, v0
	v_exp_f32_e32 v81, v1
	v_sub_f32_e32 v1, v6, v38
	v_add_f32_e32 v0, v76, v0
	v_exp_f32_e32 v78, v1
	v_sub_f32_e32 v1, v7, v38
	v_add_f32_e32 v0, v77, v0
	v_exp_f32_e32 v80, v1
	v_sub_f32_e32 v1, v42, v38
	v_add_f32_e32 v0, v79, v0
	v_exp_f32_e32 v66, v1
	v_sub_f32_e32 v1, v43, v38
	v_add_f32_e32 v0, v81, v0
	v_exp_f32_e32 v67, v1
	v_sub_f32_e32 v1, v44, v38
	v_add_f32_e32 v0, v78, v0
	v_exp_f32_e32 v68, v1
	v_sub_f32_e32 v1, v45, v38
	v_add_f32_e32 v0, v80, v0
	v_exp_f32_e32 v69, v1
	v_sub_f32_e32 v1, v46, v38
	v_add_f32_e32 v0, v66, v0
	v_exp_f32_e32 v71, v1
	v_sub_f32_e32 v1, v47, v38
	v_add_f32_e32 v0, v67, v0
	v_exp_f32_e32 v73, v1
	v_sub_f32_e32 v1, v48, v38
	v_add_f32_e32 v0, v68, v0
	v_exp_f32_e32 v70, v1
	v_sub_f32_e32 v1, v49, v38
	v_add_f32_e32 v0, v69, v0
	v_exp_f32_e32 v72, v1
	v_sub_f32_e32 v1, v54, v38
	v_add_f32_e32 v0, v71, v0
	v_exp_f32_e32 v58, v1
	v_sub_f32_e32 v1, v55, v38
	v_add_f32_e32 v0, v73, v0
	v_exp_f32_e32 v59, v1
	v_sub_f32_e32 v1, v56, v38
	v_add_f32_e32 v0, v70, v0
	v_exp_f32_e32 v60, v1
	v_sub_f32_e32 v1, v57, v38
	v_add_f32_e32 v0, v72, v0
	v_exp_f32_e32 v61, v1
	v_sub_f32_e32 v1, v34, v38
	v_add_f32_e32 v0, v58, v0
	v_exp_f32_e32 v63, v1
	v_sub_f32_e32 v1, v35, v38
	v_add_f32_e32 v0, v59, v0
	v_exp_f32_e32 v65, v1
	v_sub_f32_e32 v1, v62, v38
	v_add_f32_e32 v0, v60, v0
	v_exp_f32_e32 v62, v1
	v_sub_f32_e32 v1, v64, v38
	v_add_f32_e32 v0, v61, v0
	v_exp_f32_e32 v64, v1
	v_sub_f32_e32 v1, v102, v38
	v_add_f32_e32 v0, v63, v0
	v_exp_f32_e32 v50, v1
	v_sub_f32_e32 v1, v103, v38
	v_add_f32_e32 v0, v65, v0
	v_exp_f32_e32 v51, v1
	v_sub_f32_e32 v1, v104, v38
	v_add_f32_e32 v0, v62, v0
	v_exp_f32_e32 v52, v1
	v_sub_f32_e32 v1, v105, v38
	v_add_f32_e32 v0, v64, v0
	v_exp_f32_e32 v53, v1
	v_sub_f32_e32 v1, v106, v38
	v_add_f32_e32 v0, v50, v0
	v_exp_f32_e32 v55, v1
	v_sub_f32_e32 v1, v107, v38
	v_add_f32_e32 v0, v51, v0
	v_exp_f32_e32 v57, v1
	v_sub_f32_e32 v1, v108, v38
	v_add_f32_e32 v0, v52, v0
	v_exp_f32_e32 v54, v1
	v_sub_f32_e32 v1, v109, v38
	v_add_f32_e32 v0, v53, v0
	v_exp_f32_e32 v56, v1
	v_sub_f32_e32 v1, v110, v38
	v_add_f32_e32 v0, v55, v0
	v_exp_f32_e32 v42, v1
	v_sub_f32_e32 v1, v111, v38
	v_add_f32_e32 v0, v57, v0
	v_exp_f32_e32 v43, v1
	v_sub_f32_e32 v1, v112, v38
	v_add_f32_e32 v0, v54, v0
	v_exp_f32_e32 v44, v1
	v_sub_f32_e32 v1, v113, v38
	v_add_f32_e32 v0, v56, v0
	v_exp_f32_e32 v45, v1
	v_sub_f32_e32 v1, v114, v38
	v_add_f32_e32 v0, v42, v0
	v_exp_f32_e32 v47, v1
	v_sub_f32_e32 v1, v115, v38
	v_add_f32_e32 v0, v43, v0
	v_exp_f32_e32 v49, v1
	v_sub_f32_e32 v1, v116, v38
	v_add_f32_e32 v0, v44, v0
	v_exp_f32_e32 v46, v1
	v_sub_f32_e32 v1, v16, v38
	v_add_f32_e32 v0, v45, v0
	v_exp_f32_e32 v48, v1
	v_add_f32_e32 v0, v47, v0
	v_add_f32_e32 v0, v49, v0
	v_add_f32_e32 v0, v46, v0
	v_add_f32_e32 v0, v48, v0
	ds_bpermute_b32 v1, v100, v0
	v_cvt_pk_bf16_f32 v2, v8, v9
	v_cvt_pk_bf16_f32 v3, v10, v11
	s_waitcnt lgkmcnt(0)
	v_add_f32_e32 v39, v0, v1
	ds_bpermute_b32 v40, v101, v39
	v_lshrrev_b32_e32 v0, 2, v32
	v_or_b32_e32 v0, v83, v0
	v_lshlrev_b32_e32 v1, 3, v98
	v_mul_u32_u24_e32 v0, 0x120, v0
	v_and_b32_e32 v1, 24, v1
	v_add3_u32 v41, s27, v0, v1
	v_cvt_pk_bf16_f32 v0, v12, v13
	v_cvt_pk_bf16_f32 v1, v14, v15
	s_cbranch_vccnz .LBB0_1333
	ds_read_b64_tr_b16 v[4:5], v41
	ds_read_b64_tr_b16 v[8:9], v41 offset:32
	ds_read_b64_tr_b16 v[12:13], v41 offset:64
	ds_read_b64_tr_b16 v[16:17], v41 offset:96
	ds_read_b64_tr_b16 v[6:7], v41 offset:4608
	ds_read_b64_tr_b16 v[10:11], v41 offset:4640
	ds_read_b64_tr_b16 v[14:15], v41 offset:4672
	ds_read_b64_tr_b16 v[18:19], v41 offset:4704
	ds_read_b64_tr_b16 v[102:103], v41 offset:128
	ds_read_b64_tr_b16 v[106:107], v41 offset:160
	ds_read_b64_tr_b16 v[110:111], v41 offset:192
	ds_read_b64_tr_b16 v[114:115], v41 offset:224
	ds_read_b64_tr_b16 v[104:105], v41 offset:4736
	ds_read_b64_tr_b16 v[108:109], v41 offset:4768
	ds_read_b64_tr_b16 v[112:113], v41 offset:4800
	ds_read_b64_tr_b16 v[116:117], v41 offset:4832
	s_waitcnt lgkmcnt(11)
	v_mfma_f32_16x16x32_bf16 v[28:31], v[4:7], v[0:3], 0
	s_waitcnt lgkmcnt(10)
	v_mfma_f32_16x16x32_bf16 v[24:27], v[8:11], v[0:3], 0
	s_waitcnt lgkmcnt(9)
	v_mfma_f32_16x16x32_bf16 v[20:23], v[12:15], v[0:3], 0
	s_waitcnt lgkmcnt(8)
	v_mfma_f32_16x16x32_bf16 v[16:19], v[16:19], v[0:3], 0
	s_waitcnt lgkmcnt(3)
	v_mfma_f32_16x16x32_bf16 v[12:15], v[102:105], v[0:3], 0
	s_waitcnt lgkmcnt(2)
	v_mfma_f32_16x16x32_bf16 v[8:11], v[106:109], v[0:3], 0
	s_waitcnt lgkmcnt(1)
	v_mfma_f32_16x16x32_bf16 v[4:7], v[110:113], v[0:3], 0
	s_waitcnt lgkmcnt(0)
	v_mfma_f32_16x16x32_bf16 v[0:3], v[114:117], v[0:3], 0
	s_branch .LBB0_1334

.LBB0_1369:
	v_readlane_b32 s8, v253, 3
	s_nop 1
	v_max_i32_e32 v16, 0x80, v82
	v_readlane_b32 s9, v253, 4
	v_lshrrev_b32_e32 v18, 2, v98
	v_add_u32_e32 v17, 0x80, v82
	v_cndmask_b32_e64 v16, v82, v16, s[8:9]
	v_and_b32_e32 v83, 12, v18
	v_cmp_lt_i32_e32 vcc, v83, v16
	v_cmp_gt_i32_e64 s[10:11], v83, v17
	s_or_b64 vcc, vcc, s[10:11]
	v_or_b32_e32 v19, 1, v83
	v_cndmask_b32_e32 v12, v12, v225, vcc
	v_cmp_lt_i32_e32 vcc, v19, v16
	v_cmp_ge_i32_e64 s[10:11], v83, v17
	s_or_b64 vcc, vcc, s[10:11]
	v_or_b32_e32 v19, 2, v83
	v_cndmask_b32_e32 v13, v13, v225, vcc
	v_cmp_lt_i32_e32 vcc, v19, v16
	v_cmp_gt_i32_e64 s[10:11], v19, v17
	s_or_b64 vcc, vcc, s[10:11]
	v_or_b32_e32 v19, 3, v18
	v_cndmask_b32_e32 v14, v14, v225, vcc
	v_cmp_lt_i32_e32 vcc, v19, v16
	v_cmp_gt_i32_e64 s[10:11], v19, v17
	s_or_b64 vcc, vcc, s[10:11]
	v_or_b32_e32 v19, 16, v83
	v_cndmask_b32_e32 v15, v15, v225, vcc
	v_cmp_lt_i32_e32 vcc, v19, v16
	v_cmp_gt_i32_e64 s[10:11], v19, v17
	s_or_b64 vcc, vcc, s[10:11]
	v_or_b32_e32 v19, 17, v83
	v_cndmask_b32_e32 v8, v8, v225, vcc
	v_cmp_lt_i32_e32 vcc, v19, v16
	v_cmp_gt_i32_e64 s[10:11], v19, v17
	s_or_b64 vcc, vcc, s[10:11]
	v_or_b32_e32 v19, 18, v83
	v_cndmask_b32_e32 v9, v9, v225, vcc
	v_cmp_lt_i32_e32 vcc, v19, v16
	v_cmp_gt_i32_e64 s[10:11], v19, v17
	s_or_b64 vcc, vcc, s[10:11]
	v_or_b32_e32 v19, 19, v18
	v_cndmask_b32_e32 v10, v10, v225, vcc
	v_cmp_lt_i32_e32 vcc, v19, v16
	v_cmp_gt_i32_e64 s[10:11], v19, v17
	s_or_b64 vcc, vcc, s[10:11]
	v_or_b32_e32 v19, 32, v83
	v_cndmask_b32_e32 v11, v11, v225, vcc
	v_cmp_lt_i32_e32 vcc, v19, v16
	v_cmp_gt_i32_e64 s[10:11], v19, v17
	s_or_b64 vcc, vcc, s[10:11]
	v_or_b32_e32 v20, 33, v83
	v_cndmask_b32_e32 v19, v42, v225, vcc
	v_cmp_lt_i32_e32 vcc, v20, v16
	v_cmp_gt_i32_e64 s[10:11], v20, v17
	s_or_b64 vcc, vcc, s[10:11]
	v_or_b32_e32 v21, 34, v83
	v_cndmask_b32_e32 v20, v43, v225, vcc
	v_cmp_lt_i32_e32 vcc, v21, v16
	v_cmp_gt_i32_e64 s[10:11], v21, v17
	s_or_b64 vcc, vcc, s[10:11]
	v_or_b32_e32 v22, 35, v18
	v_cndmask_b32_e32 v21, v44, v225, vcc
	v_cmp_lt_i32_e32 vcc, v22, v16
	v_cmp_gt_i32_e64 s[10:11], v22, v17
	s_or_b64 vcc, vcc, s[10:11]
	v_or_b32_e32 v23, 48, v83
	v_cndmask_b32_e32 v22, v45, v225, vcc
	v_cmp_lt_i32_e32 vcc, v23, v16
	v_cmp_gt_i32_e64 s[10:11], v23, v17
	s_or_b64 vcc, vcc, s[10:11]
	v_or_b32_e32 v23, 49, v83
	v_cndmask_b32_e32 v0, v0, v225, vcc
	v_cmp_lt_i32_e32 vcc, v23, v16
	v_cmp_gt_i32_e64 s[10:11], v23, v17
	s_or_b64 vcc, vcc, s[10:11]
	v_or_b32_e32 v23, 50, v83
	v_cndmask_b32_e32 v1, v1, v225, vcc
	v_cmp_lt_i32_e32 vcc, v23, v16
	v_cmp_gt_i32_e64 s[10:11], v23, v17
	s_or_b64 vcc, vcc, s[10:11]
	v_or_b32_e32 v23, 51, v18
	v_cndmask_b32_e32 v2, v2, v225, vcc
	v_cmp_lt_i32_e32 vcc, v23, v16
	v_cmp_gt_i32_e64 s[10:11], v23, v17
	s_or_b64 vcc, vcc, s[10:11]
	v_or_b32_e32 v23, 64, v83
	v_cndmask_b32_e32 v3, v3, v225, vcc
	v_cmp_lt_i32_e32 vcc, v23, v16
	v_cmp_gt_i32_e64 s[10:11], v23, v17
	s_or_b64 vcc, vcc, s[10:11]
	v_or_b32_e32 v24, 0x41, v83
	v_cndmask_b32_e32 v23, v46, v225, vcc
	v_cmp_lt_i32_e32 vcc, v24, v16
	v_cmp_gt_i32_e64 s[10:11], v24, v17
	s_or_b64 vcc, vcc, s[10:11]
	v_or_b32_e32 v25, 0x42, v83
	v_cndmask_b32_e32 v24, v47, v225, vcc
	v_cmp_lt_i32_e32 vcc, v25, v16
	v_cmp_gt_i32_e64 s[10:11], v25, v17
	s_or_b64 vcc, vcc, s[10:11]
	v_or_b32_e32 v26, 0x43, v18
	v_cndmask_b32_e32 v25, v48, v225, vcc
	v_cmp_lt_i32_e32 vcc, v26, v16
	v_cmp_gt_i32_e64 s[10:11], v26, v17
	s_or_b64 vcc, vcc, s[10:11]
	v_or_b32_e32 v27, 0x50, v83
	v_cndmask_b32_e32 v26, v49, v225, vcc
	v_cmp_lt_i32_e32 vcc, v27, v16
	v_cmp_gt_i32_e64 s[10:11], v27, v17
	s_or_b64 vcc, vcc, s[10:11]
	v_or_b32_e32 v28, 0x51, v83
	v_cndmask_b32_e32 v27, v38, v225, vcc
	v_cmp_lt_i32_e32 vcc, v28, v16
	v_cmp_gt_i32_e64 s[10:11], v28, v17
	s_or_b64 vcc, vcc, s[10:11]
	v_or_b32_e32 v29, 0x52, v83
	v_cndmask_b32_e32 v28, v39, v225, vcc
	v_cmp_lt_i32_e32 vcc, v29, v16
	v_cmp_gt_i32_e64 s[10:11], v29, v17
	s_or_b64 vcc, vcc, s[10:11]
	v_or_b32_e32 v30, 0x53, v18
	v_cndmask_b32_e32 v29, v40, v225, vcc
	v_cmp_lt_i32_e32 vcc, v30, v16
	v_cmp_gt_i32_e64 s[10:11], v30, v17
	s_or_b64 vcc, vcc, s[10:11]
	v_or_b32_e32 v31, 0x60, v83
	v_cndmask_b32_e32 v30, v41, v225, vcc
	v_cmp_lt_i32_e32 vcc, v31, v16
	v_cmp_gt_i32_e64 s[10:11], v31, v17
	s_or_b64 vcc, vcc, s[10:11]
	v_or_b32_e32 v32, 0x61, v83
	v_cndmask_b32_e32 v31, v58, v225, vcc
	v_cmp_lt_i32_e32 vcc, v32, v16
	v_cmp_gt_i32_e64 s[10:11], v32, v17
	s_or_b64 vcc, vcc, s[10:11]
	v_or_b32_e32 v38, 0x62, v83
	v_cndmask_b32_e32 v32, v59, v225, vcc
	v_cmp_lt_i32_e32 vcc, v38, v16
	v_cmp_gt_i32_e64 s[10:11], v38, v17
	s_or_b64 vcc, vcc, s[10:11]
	v_or_b32_e32 v38, 0x63, v18
	v_cndmask_b32_e32 v39, v60, v225, vcc
	v_cmp_lt_i32_e32 vcc, v38, v16
	v_cmp_gt_i32_e64 s[10:11], v38, v17
	s_or_b64 vcc, vcc, s[10:11]
	v_or_b32_e32 v38, 0x70, v83
	v_cndmask_b32_e32 v40, v61, v225, vcc
	v_cmp_lt_i32_e32 vcc, v38, v16
	v_cmp_gt_i32_e64 s[10:11], v38, v17
	s_or_b64 vcc, vcc, s[10:11]
	v_or_b32_e32 v38, 0x71, v83
	v_cndmask_b32_e32 v4, v4, v225, vcc
	v_cmp_lt_i32_e32 vcc, v38, v16
	v_cmp_gt_i32_e64 s[10:11], v38, v17
	s_or_b64 vcc, vcc, s[10:11]
	v_or_b32_e32 v38, 0x72, v83
	v_cndmask_b32_e32 v5, v5, v225, vcc
	v_cmp_lt_i32_e32 vcc, v38, v16
	v_cmp_gt_i32_e64 s[10:11], v38, v17
	s_or_b64 vcc, vcc, s[10:11]
	v_or_b32_e32 v38, 0x73, v18
	v_cndmask_b32_e32 v6, v6, v225, vcc
	v_cmp_lt_i32_e32 vcc, v38, v16
	v_cmp_gt_i32_e64 s[10:11], v38, v17
	s_or_b64 vcc, vcc, s[10:11]
	v_or_b32_e32 v38, 0x80, v83
	v_cndmask_b32_e32 v7, v7, v225, vcc
	v_cmp_lt_i32_e32 vcc, v38, v16
	v_cmp_gt_i32_e64 s[10:11], v83, v82
	s_or_b64 vcc, s[10:11], vcc
	v_or_b32_e32 v38, 0x81, v83
	v_cndmask_b32_e32 v41, v62, v225, vcc
	v_cmp_lt_i32_e32 vcc, v38, v16
	v_cmp_gt_i32_e64 s[10:11], v38, v17
	s_or_b64 vcc, vcc, s[10:11]
	v_or_b32_e32 v38, 0x82, v83
	v_cndmask_b32_e32 v42, v63, v225, vcc
	v_cmp_lt_i32_e32 vcc, v38, v16
	v_cmp_gt_i32_e64 s[10:11], v38, v17
	s_or_b64 vcc, vcc, s[10:11]
	v_or_b32_e32 v38, 0x83, v18
	v_cndmask_b32_e32 v43, v64, v225, vcc
	v_cmp_lt_i32_e32 vcc, v38, v16
	v_cmp_gt_i32_e64 s[10:11], v38, v17
	s_or_b64 vcc, vcc, s[10:11]
	v_or_b32_e32 v38, 0x90, v83
	v_cndmask_b32_e32 v44, v65, v225, vcc
	v_cmp_lt_i32_e32 vcc, v38, v16
	v_cmp_gt_i32_e64 s[10:11], v38, v17
	s_or_b64 vcc, vcc, s[10:11]
	v_or_b32_e32 v38, 0x91, v83
	v_cndmask_b32_e32 v45, v54, v225, vcc
	v_cmp_lt_i32_e32 vcc, v38, v16
	v_cmp_gt_i32_e64 s[10:11], v38, v17
	s_or_b64 vcc, vcc, s[10:11]
	v_or_b32_e32 v38, 0x92, v83
	v_cndmask_b32_e32 v46, v55, v225, vcc
	v_cmp_lt_i32_e32 vcc, v38, v16
	v_cmp_gt_i32_e64 s[10:11], v38, v17
	s_or_b64 vcc, vcc, s[10:11]
	v_or_b32_e32 v38, 0x93, v18
	v_cndmask_b32_e32 v47, v56, v225, vcc
	v_cmp_lt_i32_e32 vcc, v38, v16
	v_cmp_gt_i32_e64 s[10:11], v38, v17
	s_or_b64 vcc, vcc, s[10:11]
	v_or_b32_e32 v38, 0xa0, v83
	v_cndmask_b32_e32 v48, v57, v225, vcc
	v_cmp_lt_i32_e32 vcc, v38, v16
	v_cmp_gt_i32_e64 s[10:11], v38, v17
	s_or_b64 vcc, vcc, s[10:11]
	v_or_b32_e32 v38, 0xa1, v83
	v_cndmask_b32_e32 v49, v70, v225, vcc
	v_cmp_lt_i32_e32 vcc, v38, v16
	v_cmp_gt_i32_e64 s[10:11], v38, v17
	s_or_b64 vcc, vcc, s[10:11]
	v_or_b32_e32 v38, 0xa2, v83
	v_cndmask_b32_e32 v54, v71, v225, vcc
	v_cmp_lt_i32_e32 vcc, v38, v16
	v_cmp_gt_i32_e64 s[10:11], v38, v17
	s_or_b64 vcc, vcc, s[10:11]
	v_or_b32_e32 v38, 0xa3, v18
	v_cndmask_b32_e32 v55, v72, v225, vcc
	v_cmp_lt_i32_e32 vcc, v38, v16
	v_cmp_gt_i32_e64 s[10:11], v38, v17
	s_or_b64 vcc, vcc, s[10:11]
	v_or_b32_e32 v38, 0xb0, v83
	v_cndmask_b32_e32 v56, v73, v225, vcc
	v_cmp_lt_i32_e32 vcc, v38, v16
	v_cmp_gt_i32_e64 s[10:11], v38, v17
	s_or_b64 vcc, vcc, s[10:11]
	v_or_b32_e32 v38, 0xb1, v83
	v_cndmask_b32_e32 v34, v34, v225, vcc
	v_cmp_lt_i32_e32 vcc, v38, v16
	v_cmp_gt_i32_e64 s[10:11], v38, v17
	s_or_b64 vcc, vcc, s[10:11]
	v_or_b32_e32 v38, 0xb2, v83
	v_cndmask_b32_e32 v35, v35, v225, vcc
	v_cmp_lt_i32_e32 vcc, v38, v16
	v_cmp_gt_i32_e64 s[10:11], v38, v17
	s_or_b64 vcc, vcc, s[10:11]
	v_cndmask_b32_e32 v57, v36, v225, vcc
	v_or_b32_e32 v36, 0xb3, v18
	v_cmp_lt_i32_e32 vcc, v36, v16
	v_cmp_gt_i32_e64 s[10:11], v36, v17
	s_or_b64 vcc, vcc, s[10:11]
	v_or_b32_e32 v36, 0xc0, v83
	v_cndmask_b32_e32 v64, v37, v225, vcc
	v_cmp_lt_i32_e32 vcc, v36, v16
	v_cmp_gt_i32_e64 s[10:11], v36, v17
	s_or_b64 vcc, vcc, s[10:11]
	v_or_b32_e32 v36, 0xc1, v83
	v_cndmask_b32_e32 v103, v74, v225, vcc
	v_cmp_lt_i32_e32 vcc, v36, v16
	v_cmp_gt_i32_e64 s[10:11], v36, v17
	s_or_b64 vcc, vcc, s[10:11]
	v_or_b32_e32 v36, 0xc2, v83
	v_cndmask_b32_e32 v104, v75, v225, vcc
	v_cmp_lt_i32_e32 vcc, v36, v16
	v_cmp_gt_i32_e64 s[10:11], v36, v17
	s_or_b64 vcc, vcc, s[10:11]
	v_or_b32_e32 v36, 0xc3, v18
	v_cndmask_b32_e32 v105, v76, v225, vcc
	v_cmp_lt_i32_e32 vcc, v36, v16
	v_cmp_gt_i32_e64 s[10:11], v36, v17
	s_or_b64 vcc, vcc, s[10:11]
	v_or_b32_e32 v36, 0xd0, v83
	v_cndmask_b32_e32 v106, v77, v225, vcc
	v_cmp_lt_i32_e32 vcc, v36, v16
	v_cmp_gt_i32_e64 s[10:11], v36, v17
	s_or_b64 vcc, vcc, s[10:11]
	v_or_b32_e32 v36, 0xd1, v83
	v_cndmask_b32_e32 v107, v66, v225, vcc
	v_cmp_lt_i32_e32 vcc, v36, v16
	v_cmp_gt_i32_e64 s[10:11], v36, v17
	s_or_b64 vcc, vcc, s[10:11]
	v_or_b32_e32 v36, 0xd2, v83
	v_cndmask_b32_e32 v108, v67, v225, vcc
	v_cmp_lt_i32_e32 vcc, v36, v16
	v_cmp_gt_i32_e64 s[10:11], v36, v17
	s_or_b64 vcc, vcc, s[10:11]
	v_or_b32_e32 v36, 0xd3, v18
	v_cndmask_b32_e32 v109, v68, v225, vcc
	v_cmp_lt_i32_e32 vcc, v36, v16
	v_cmp_gt_i32_e64 s[10:11], v36, v17
	s_or_b64 vcc, vcc, s[10:11]
	v_or_b32_e32 v36, 0xe0, v83
	v_cndmask_b32_e32 v110, v69, v225, vcc
	v_cmp_lt_i32_e32 vcc, v36, v16
	v_cmp_gt_i32_e64 s[10:11], v36, v17
	s_or_b64 vcc, vcc, s[10:11]
	v_or_b32_e32 v36, 0xe1, v83
	v_cndmask_b32_e32 v111, v78, v225, vcc
	v_cmp_lt_i32_e32 vcc, v36, v16
	v_cmp_gt_i32_e64 s[10:11], v36, v17
	s_or_b64 vcc, vcc, s[10:11]
	v_or_b32_e32 v36, 0xe2, v83
	v_cndmask_b32_e32 v112, v79, v225, vcc
	v_cmp_lt_i32_e32 vcc, v36, v16
	v_cmp_gt_i32_e64 s[10:11], v36, v17
	s_or_b64 vcc, vcc, s[10:11]
	v_or_b32_e32 v36, 0xe3, v18
	v_cndmask_b32_e32 v113, v80, v225, vcc
	v_cmp_lt_i32_e32 vcc, v36, v16
	v_cmp_gt_i32_e64 s[10:11], v36, v17
	s_or_b64 vcc, vcc, s[10:11]
	v_or_b32_e32 v36, 0xf0, v83
	v_cndmask_b32_e32 v114, v81, v225, vcc
	v_cmp_lt_i32_e32 vcc, v36, v16
	v_cmp_gt_i32_e64 s[10:11], v36, v17
	s_or_b64 vcc, vcc, s[10:11]
	v_or_b32_e32 v36, 0xf1, v83
	v_cndmask_b32_e32 v115, v50, v225, vcc
	v_cmp_lt_i32_e32 vcc, v36, v16
	v_cmp_gt_i32_e64 s[10:11], v36, v17
	s_or_b64 vcc, vcc, s[10:11]
	v_or_b32_e32 v36, 0xf2, v83
	v_cndmask_b32_e32 v116, v51, v225, vcc
	v_cmp_lt_i32_e32 vcc, v36, v16
	v_cmp_gt_i32_e64 s[10:11], v36, v17
	s_or_b64 vcc, vcc, s[10:11]
	v_or_b32_e32 v18, 0xf3, v18
	v_cndmask_b32_e32 v117, v52, v225, vcc
	v_cmp_lt_i32_e32 vcc, v18, v16
	v_cmp_gt_i32_e64 s[10:11], v18, v17
	v_max_f32_e32 v17, v12, v13
	v_max_f32_e32 v18, v14, v15
	s_mov_b32 s8, 0xff61b1e6
	v_max3_f32 v17, v17, v18, s8
	v_max_f32_e32 v18, v8, v9
	v_max_f32_e32 v36, v10, v11
	v_max3_f32 v17, v18, v36, v17
	v_max_f32_e32 v18, v19, v20
	v_max_f32_e32 v36, v21, v22
	v_max3_f32 v17, v18, v36, v17
	v_max_f32_e32 v18, v0, v1
	v_max_f32_e32 v36, v2, v3
	v_max3_f32 v17, v18, v36, v17
	v_max_f32_e32 v18, v23, v24
	v_max_f32_e32 v36, v25, v26
	v_max3_f32 v17, v18, v36, v17
	v_max_f32_e32 v18, v27, v28
	v_max_f32_e32 v36, v29, v30
	v_max3_f32 v17, v18, v36, v17
	v_max_f32_e32 v18, v31, v32
	v_max_f32_e32 v36, v39, v40
	v_max3_f32 v17, v18, v36, v17
	v_max_f32_e32 v18, v4, v5
	v_max_f32_e32 v36, v6, v7
	v_max3_f32 v17, v18, v36, v17
	v_max_f32_e32 v18, v41, v42
	v_max_f32_e32 v36, v43, v44
	v_max3_f32 v17, v18, v36, v17
	v_max_f32_e32 v18, v45, v46
	v_max_f32_e32 v36, v47, v48
	v_max3_f32 v17, v18, v36, v17
	v_max_f32_e32 v18, v49, v54
	v_max_f32_e32 v36, v55, v56
	v_max3_f32 v17, v18, v36, v17
	v_max_f32_e32 v18, v34, v35
	v_max_f32_e32 v36, v57, v64
	v_max3_f32 v17, v18, v36, v17
	v_max_f32_e32 v18, v103, v104
	v_max_f32_e32 v36, v105, v106
	v_max3_f32 v17, v18, v36, v17
	v_max_f32_e32 v18, v107, v108
	v_max_f32_e32 v36, v109, v110
	v_max3_f32 v17, v18, v36, v17
	v_max_f32_e32 v18, v111, v112
	s_or_b64 vcc, vcc, s[10:11]
	v_max_f32_e32 v36, v113, v114
	v_cndmask_b32_e32 v16, v53, v225, vcc
	v_max3_f32 v17, v18, v36, v17
	v_max_f32_e32 v18, v115, v116
	v_max_f32_e32 v36, v117, v16
	v_max3_f32 v17, v18, v36, v17
	ds_bpermute_b32 v18, v100, v17
	s_andn2_b64 vcc, exec, s[44:45]
	s_waitcnt lgkmcnt(0)
	v_max_f32_e32 v17, v17, v18
	ds_bpermute_b32 v18, v101, v17
	s_waitcnt lgkmcnt(0)
	v_max_f32_e32 v38, v17, v18
	v_sub_f32_e32 v12, v12, v38
	v_exp_f32_e32 v12, v12
	v_sub_f32_e32 v13, v13, v38
	v_exp_f32_e32 v13, v13
	v_sub_f32_e32 v14, v14, v38
	v_exp_f32_e32 v14, v14
	v_sub_f32_e32 v15, v15, v38
	v_exp_f32_e32 v15, v15
	v_sub_f32_e32 v8, v8, v38
	v_add_f32_e32 v17, 0, v12
	v_exp_f32_e32 v8, v8
	v_sub_f32_e32 v9, v9, v38
	v_add_f32_e32 v17, v13, v17
	v_exp_f32_e32 v9, v9
	v_sub_f32_e32 v10, v10, v38
	v_add_f32_e32 v17, v14, v17
	v_exp_f32_e32 v10, v10
	v_sub_f32_e32 v11, v11, v38
	v_add_f32_e32 v17, v15, v17
	v_exp_f32_e32 v11, v11
	v_sub_f32_e32 v18, v19, v38
	v_add_f32_e32 v17, v8, v17
	v_exp_f32_e32 v36, v18
	v_sub_f32_e32 v18, v20, v38
	v_add_f32_e32 v17, v9, v17
	v_exp_f32_e32 v37, v18
	v_sub_f32_e32 v18, v21, v38
	v_add_f32_e32 v17, v10, v17
	v_exp_f32_e32 v94, v18
	v_sub_f32_e32 v18, v22, v38
	v_add_f32_e32 v17, v11, v17
	v_exp_f32_e32 v95, v18
	v_sub_f32_e32 v0, v0, v38
	v_add_f32_e32 v17, v36, v17
	v_exp_f32_e32 v97, v0
	v_sub_f32_e32 v0, v1, v38
	v_add_f32_e32 v17, v37, v17
	v_exp_f32_e32 v102, v0
	v_sub_f32_e32 v0, v2, v38
	v_add_f32_e32 v17, v94, v17
	v_exp_f32_e32 v96, v0
	v_sub_f32_e32 v0, v3, v38
	v_add_f32_e32 v17, v95, v17
	v_exp_f32_e32 v99, v0
	v_sub_f32_e32 v1, v23, v38
	v_add_f32_e32 v0, v97, v17
	v_exp_f32_e32 v86, v1
	v_sub_f32_e32 v1, v24, v38
	v_add_f32_e32 v0, v102, v0
	v_exp_f32_e32 v87, v1
	v_sub_f32_e32 v1, v25, v38
	v_add_f32_e32 v0, v96, v0
	v_exp_f32_e32 v88, v1
	v_sub_f32_e32 v1, v26, v38
	v_add_f32_e32 v0, v99, v0
	v_exp_f32_e32 v89, v1
	v_sub_f32_e32 v1, v27, v38
	v_add_f32_e32 v0, v86, v0
	v_exp_f32_e32 v91, v1
	v_sub_f32_e32 v1, v28, v38
	v_add_f32_e32 v0, v87, v0
	v_exp_f32_e32 v93, v1
	v_sub_f32_e32 v1, v29, v38
	v_add_f32_e32 v0, v88, v0
	v_exp_f32_e32 v90, v1
	v_sub_f32_e32 v1, v30, v38
	v_add_f32_e32 v0, v89, v0
	v_exp_f32_e32 v92, v1
	v_sub_f32_e32 v1, v31, v38
	v_add_f32_e32 v0, v91, v0
	v_exp_f32_e32 v74, v1
	v_sub_f32_e32 v1, v32, v38
	v_add_f32_e32 v0, v93, v0
	v_exp_f32_e32 v75, v1
	v_sub_f32_e32 v1, v39, v38
	v_add_f32_e32 v0, v90, v0
	v_exp_f32_e32 v76, v1
	v_sub_f32_e32 v1, v40, v38
	v_add_f32_e32 v0, v92, v0
	v_exp_f32_e32 v77, v1
	v_sub_f32_e32 v1, v4, v38
	v_add_f32_e32 v0, v74, v0
	v_exp_f32_e32 v79, v1
	v_sub_f32_e32 v1, v5, v38
	v_add_f32_e32 v0, v75, v0
	v_exp_f32_e32 v81, v1
	v_sub_f32_e32 v1, v6, v38
	v_add_f32_e32 v0, v76, v0
	v_exp_f32_e32 v78, v1
	v_sub_f32_e32 v1, v7, v38
	v_add_f32_e32 v0, v77, v0
	v_exp_f32_e32 v80, v1
	v_sub_f32_e32 v1, v41, v38
	v_add_f32_e32 v0, v79, v0
	v_exp_f32_e32 v66, v1
	v_sub_f32_e32 v1, v42, v38
	v_add_f32_e32 v0, v81, v0
	v_exp_f32_e32 v67, v1
	v_sub_f32_e32 v1, v43, v38
	v_add_f32_e32 v0, v78, v0
	v_exp_f32_e32 v68, v1
	v_sub_f32_e32 v1, v44, v38
	v_add_f32_e32 v0, v80, v0
	v_exp_f32_e32 v69, v1
	v_sub_f32_e32 v1, v45, v38
	v_add_f32_e32 v0, v66, v0
	v_exp_f32_e32 v71, v1
	v_sub_f32_e32 v1, v46, v38
	v_add_f32_e32 v0, v67, v0
	v_exp_f32_e32 v73, v1
	v_sub_f32_e32 v1, v47, v38
	v_add_f32_e32 v0, v68, v0
	v_exp_f32_e32 v70, v1
	v_sub_f32_e32 v1, v48, v38
	v_add_f32_e32 v0, v69, v0
	v_exp_f32_e32 v72, v1
	v_sub_f32_e32 v1, v49, v38
	v_add_f32_e32 v0, v71, v0
	v_exp_f32_e32 v58, v1
	v_sub_f32_e32 v1, v54, v38
	v_add_f32_e32 v0, v73, v0
	v_exp_f32_e32 v59, v1
	v_sub_f32_e32 v1, v55, v38
	v_add_f32_e32 v0, v70, v0
	v_exp_f32_e32 v60, v1
	v_sub_f32_e32 v1, v56, v38
	v_add_f32_e32 v0, v72, v0
	v_exp_f32_e32 v61, v1
	v_sub_f32_e32 v1, v34, v38
	v_add_f32_e32 v0, v58, v0
	v_exp_f32_e32 v63, v1
	v_sub_f32_e32 v1, v35, v38
	v_add_f32_e32 v0, v59, v0
	v_exp_f32_e32 v65, v1
	v_sub_f32_e32 v1, v57, v38
	v_add_f32_e32 v0, v60, v0
	v_exp_f32_e32 v62, v1
	v_sub_f32_e32 v1, v64, v38
	v_add_f32_e32 v0, v61, v0
	v_exp_f32_e32 v64, v1
	v_sub_f32_e32 v1, v103, v38
	v_add_f32_e32 v0, v63, v0
	v_exp_f32_e32 v50, v1
	v_sub_f32_e32 v1, v104, v38
	v_add_f32_e32 v0, v65, v0
	v_exp_f32_e32 v51, v1
	v_sub_f32_e32 v1, v105, v38
	v_add_f32_e32 v0, v62, v0
	v_exp_f32_e32 v52, v1
	v_sub_f32_e32 v1, v106, v38
	v_add_f32_e32 v0, v64, v0
	v_exp_f32_e32 v53, v1
	v_sub_f32_e32 v1, v107, v38
	v_add_f32_e32 v0, v50, v0
	v_exp_f32_e32 v55, v1
	v_sub_f32_e32 v1, v108, v38
	v_add_f32_e32 v0, v51, v0
	v_exp_f32_e32 v57, v1
	v_sub_f32_e32 v1, v109, v38
	v_add_f32_e32 v0, v52, v0
	v_exp_f32_e32 v54, v1
	v_sub_f32_e32 v1, v110, v38
	v_add_f32_e32 v0, v53, v0
	v_exp_f32_e32 v56, v1
	v_sub_f32_e32 v1, v111, v38
	v_add_f32_e32 v0, v55, v0
	v_exp_f32_e32 v42, v1
	v_sub_f32_e32 v1, v112, v38
	v_add_f32_e32 v0, v57, v0
	v_exp_f32_e32 v43, v1
	v_sub_f32_e32 v1, v113, v38
	v_add_f32_e32 v0, v54, v0
	v_exp_f32_e32 v44, v1
	v_sub_f32_e32 v1, v114, v38
	v_add_f32_e32 v0, v56, v0
	v_exp_f32_e32 v45, v1
	v_sub_f32_e32 v1, v115, v38
	v_add_f32_e32 v0, v42, v0
	v_exp_f32_e32 v47, v1
	v_sub_f32_e32 v1, v116, v38
	v_add_f32_e32 v0, v43, v0
	v_exp_f32_e32 v49, v1
	v_sub_f32_e32 v1, v117, v38
	v_add_f32_e32 v0, v44, v0
	v_exp_f32_e32 v46, v1
	v_sub_f32_e32 v1, v16, v38
	v_add_f32_e32 v0, v45, v0
	v_exp_f32_e32 v48, v1
	v_add_f32_e32 v0, v47, v0
	v_add_f32_e32 v0, v49, v0
	v_add_f32_e32 v0, v46, v0
	v_add_f32_e32 v0, v48, v0
	ds_bpermute_b32 v1, v100, v0
	v_cvt_pk_bf16_f32 v2, v8, v9
	v_cvt_pk_bf16_f32 v3, v10, v11
	s_waitcnt lgkmcnt(0)
	v_add_f32_e32 v39, v0, v1
	ds_bpermute_b32 v40, v101, v39
	v_lshrrev_b32_e32 v0, 2, v85
	v_or_b32_e32 v0, v83, v0
	v_lshlrev_b32_e32 v1, 3, v98
	v_mul_u32_u24_e32 v0, 0x120, v0
	v_and_b32_e32 v1, 24, v1
	v_add3_u32 v41, s27, v0, v1
	v_cvt_pk_bf16_f32 v0, v12, v13
	v_cvt_pk_bf16_f32 v1, v14, v15
	s_cbranch_vccnz .LBB0_1371
	ds_read_b64_tr_b16 v[4:5], v41
	ds_read_b64_tr_b16 v[8:9], v41 offset:32
	ds_read_b64_tr_b16 v[12:13], v41 offset:64
	ds_read_b64_tr_b16 v[16:17], v41 offset:96
	ds_read_b64_tr_b16 v[6:7], v41 offset:4608
	ds_read_b64_tr_b16 v[10:11], v41 offset:4640
	ds_read_b64_tr_b16 v[14:15], v41 offset:4672
	ds_read_b64_tr_b16 v[18:19], v41 offset:4704
	ds_read_b64_tr_b16 v[104:105], v41 offset:128
	ds_read_b64_tr_b16 v[108:109], v41 offset:160
	ds_read_b64_tr_b16 v[112:113], v41 offset:192
	ds_read_b64_tr_b16 v[116:117], v41 offset:224
	ds_read_b64_tr_b16 v[106:107], v41 offset:4736
	ds_read_b64_tr_b16 v[110:111], v41 offset:4768
	ds_read_b64_tr_b16 v[114:115], v41 offset:4800
	ds_read_b64_tr_b16 v[118:119], v41 offset:4832
	s_waitcnt lgkmcnt(11)
	v_mfma_f32_16x16x32_bf16 v[28:31], v[4:7], v[0:3], 0
	s_waitcnt lgkmcnt(10)
	v_mfma_f32_16x16x32_bf16 v[24:27], v[8:11], v[0:3], 0
	s_waitcnt lgkmcnt(9)
	v_mfma_f32_16x16x32_bf16 v[20:23], v[12:15], v[0:3], 0
	s_waitcnt lgkmcnt(8)
	v_mfma_f32_16x16x32_bf16 v[16:19], v[16:19], v[0:3], 0
	s_waitcnt lgkmcnt(3)
	v_mfma_f32_16x16x32_bf16 v[12:15], v[104:107], v[0:3], 0
	s_waitcnt lgkmcnt(2)
	v_mfma_f32_16x16x32_bf16 v[8:11], v[108:111], v[0:3], 0
	s_waitcnt lgkmcnt(1)
	v_mfma_f32_16x16x32_bf16 v[4:7], v[112:115], v[0:3], 0
	s_waitcnt lgkmcnt(0)
	v_mfma_f32_16x16x32_bf16 v[0:3], v[116:119], v[0:3], 0
	s_branch .LBB0_1372
